# st2 epilogue 3-tap conv via v_fmac_f32_dpp as well
# speedup vs baseline: 1.0048x; 1.0022x over previous
; HD float2 cmul(float2 a, float2 b){ return make_float2(a.x*b.x - a.y*b.y, a.x*b.y + a.y*b.x); }
; HD float2 cmulc(float2 a, float2 b){ return make_float2(a.x*b.x + a.y*b.y, a.y*b.x - a.x*b.y); }
; template<bool INV, bool NOTW>
; HD void bf4c(float2* Z, int i0, int i1, int i2, int i3, float2 w1, float2 w2, float2 w3){
;   float2 a0=Z[i0], a1=Z[i1], a2=Z[i2], a3=Z[i3];
;   if (INV && !NOTW){ a1=cmulc(a1,w1); a2=cmulc(a2,w2); a3=cmulc(a3,w3); }
;   float2 s02=make_float2(a0.x+a2.x,a0.y+a2.y), d02=make_float2(a0.x-a2.x,a0.y-a2.y);
;   float2 s13=make_float2(a1.x+a3.x,a1.y+a3.y), d13=make_float2(a1.x-a3.x,a1.y-a3.y);
;   float2 y0=make_float2(s02.x+s13.x,s02.y+s13.y), y2=make_float2(s02.x-s13.x,s02.y-s13.y);
;   float2 ym=make_float2(d02.x+d13.y,d02.y-d13.x);
;   float2 yp=make_float2(d02.x-d13.y,d02.y+d13.x);
;   float2 y1, y3;
;   if (INV){ y1=yp; y3=ym; } else if (NOTW){ y1=ym; y3=yp; } else { y1=cmul(ym,w1); y2=cmul(y2,w2); y3=cmul(yp,w3); }
;   Z[i0]=y0; Z[i1]=y1; Z[i2]=y2; Z[i3]=y3;
; }
; HD int rev4_14(int p){ unsigned r = __brev((unsigned)p) >> 18; return (int)(((r & 0x2AAAu) >> 1) | ((r & 0x1555u) << 1)); }
; template<bool INV, int LQ, bool BARRIER=true>
; HD void fft_pass(float2* Z, const float2* twA, const float2* twB, int tid){
;   constexpr int q=1<<LQ; constexpr int tws=4096>>LQ;
;   if (LQ==12){
;     _Pragma("unroll 2") for (int i=0;i<8;++i){ int t=tid+512*i; int k=t;
;       float2 w1=cmul(twA[k>>6],twB[k&63]), w2=cmul(w1,w1), w3=cmul(w2,w1);
;       bf4c<INV,false>(Z,t,t+q,t+2*q,t+3*q,w1,w2,w3); }
;   } else if (LQ==10){
;     _Pragma("unroll") for (int e=0;e<2;++e){ int j=tid+512*e; int k=j*tws;
;       float2 w1=cmul(twA[k>>6],twB[k&63]), w2=cmul(w1,w1), w3=cmul(w2,w1);
;       _Pragma("unroll") for (int ip=0;ip<4;++ip){ int base=ip*4096+j; bf4c<INV,false>(Z,base,base+q,base+2*q,base+3*q,w1,w2,w3); } }
;   } else {
;     int j=tid&(q-1); int base0=((tid>>LQ)<<(LQ+2))+j;
;     float2 w1=make_float2(1.f,0.f), w2=w1, w3=w1;
;     if (LQ>0){ int k=j*tws; w1=cmul(twA[k>>6],twB[k&63]); w2=cmul(w1,w1); w3=cmul(w2,w1); }
;     _Pragma("unroll") for (int i=0;i<8;++i){ int base=base0+i*2048; bf4c<INV,(LQ==0)>(Z,base,base+q,base+2*q,base+3*q,w1,w2,w3); }
;   }
;   if (BARRIER) __syncthreads(); else asm volatile("s_waitcnt lgkmcnt(0)" ::: "memory");
; }
.Lmy_pf_st1:
	global_load_dwordx4 v[228:231], v232, s[98:99]
	global_load_dwordx4 v[228:231], v233, s[98:99]
	global_load_dwordx4 v[228:231], v234, s[98:99]
	global_load_dwordx4 v[228:231], v235, s[98:99]
	s_add_u32 s98, s98, 0x1000000
	s_addc_u32 s99, s99, 0
	global_load_dwordx4 v[228:231], v232, s[98:99]
	global_load_dwordx4 v[228:231], v233, s[98:99]
	global_load_dwordx4 v[228:231], v234, s[98:99]
	global_load_dwordx4 v[228:231], v235, s[98:99]
	s_waitcnt lgkmcnt(0)
	v_mov_b32_e32 v222, 0x3f6c835e
	v_mov_b32_e32 v223, 0x3ec3ef15
	v_mov_b32_e32 v224, 0x3f3504f3
	v_mov_b32_e32 v225, 0x3f3504f3
	v_and_b32_e32 v8, 15, v154
	v_lshlrev_b32_e32 v9, 3, v8
	v_add_u32_e32 v9, 0x20800, v9
	v_mov_b32_e32 v10, 0x20a00
	ds_read_b64 v[0:1], v9
	ds_read_b64 v[2:3], v10
	s_waitcnt lgkmcnt(0)
	v_pk_mul_f32 v[250:251], v[0:1], v[2:3] op_sel:[1,1] op_sel_hi:[1,0]
	v_pk_fma_f32 v[80:81], v[0:1], v[2:3], v[250:251] op_sel:[0,0,0] op_sel_hi:[0,1,1] neg_lo:[0,0,1]
	v_pk_mul_f32 v[250:251], v[80:81], v[80:81] op_sel:[1,1] op_sel_hi:[1,0]
	v_pk_fma_f32 v[82:83], v[80:81], v[80:81], v[250:251] op_sel:[0,0,0] op_sel_hi:[0,1,1] neg_lo:[0,0,1]
	v_pk_mul_f32 v[250:251], v[82:83], v[80:81] op_sel:[1,1] op_sel_hi:[1,0]
	v_pk_fma_f32 v[84:85], v[82:83], v[80:81], v[250:251] op_sel:[0,0,0] op_sel_hi:[0,1,1] neg_lo:[0,0,1]
	v_lshlrev_b32_e32 v9, 5, v8
	v_add_u32_e32 v9, 0x20800, v9
	v_mov_b32_e32 v10, 0x20a00
	ds_read_b64 v[0:1], v9
	ds_read_b64 v[2:3], v10
	s_waitcnt lgkmcnt(0)
	v_pk_mul_f32 v[250:251], v[0:1], v[2:3] op_sel:[1,1] op_sel_hi:[1,0]
	v_pk_fma_f32 v[236:237], v[0:1], v[2:3], v[250:251] op_sel:[0,0,0] op_sel_hi:[0,1,1] neg_lo:[0,0,1]
	v_pk_mul_f32 v[250:251], v[236:237], v[236:237] op_sel:[1,1] op_sel_hi:[1,0]
	v_pk_fma_f32 v[238:239], v[236:237], v[236:237], v[250:251] op_sel:[0,0,0] op_sel_hi:[0,1,1] neg_lo:[0,0,1]
	v_pk_mul_f32 v[250:251], v[238:239], v[236:237] op_sel:[1,1] op_sel_hi:[1,0]
	v_pk_fma_f32 v[240:241], v[238:239], v[236:237], v[250:251] op_sel:[0,0,0] op_sel_hi:[0,1,1] neg_lo:[0,0,1]
	v_lshrrev_b32_e32 v226, 6, v154
	v_bfe_u32 v227, v154, 4, 2
	v_lshl_add_u32 v226, v227, 3, v226
	v_lshlrev_b32_e32 v226, 8, v226
	v_and_b32_e32 v227, 15, v154
	v_add_u32_e32 v226, v226, v227
	v_lshlrev_b32_e32 v226, 3, v226
	v_add_u32_e32 v227, 0x10000, v226
	ds_read_b64 v[0:1], v226 offset:0
	ds_read_b64 v[2:3], v226 offset:128
	ds_read_b64 v[4:5], v226 offset:256
	ds_read_b64 v[6:7], v226 offset:384
	ds_read_b64 v[8:9], v226 offset:512
	ds_read_b64 v[10:11], v226 offset:640
	ds_read_b64 v[12:13], v226 offset:768
	ds_read_b64 v[14:15], v226 offset:896
	ds_read_b64 v[16:17], v226 offset:1024
	ds_read_b64 v[18:19], v226 offset:1152
	ds_read_b64 v[20:21], v226 offset:1280
	ds_read_b64 v[22:23], v226 offset:1408
	ds_read_b64 v[24:25], v226 offset:1536
	ds_read_b64 v[26:27], v226 offset:1664
	ds_read_b64 v[28:29], v226 offset:1792
	ds_read_b64 v[30:31], v226 offset:1920
	s_waitcnt lgkmcnt(12)
	v_pk_mul_f32 v[250:251], v[4:5], v[238:239] op_sel:[1,1] op_sel_hi:[0,1]
	v_pk_fma_f32 v[4:5], v[4:5], v[238:239], v[250:251] op_sel:[0,0,0] op_sel_hi:[1,0,1] neg_hi:[0,0,1]
	v_pk_mul_f32 v[250:251], v[2:3], v[236:237] op_sel:[1,1] op_sel_hi:[0,1]
	v_pk_fma_f32 v[2:3], v[2:3], v[236:237], v[250:251] op_sel:[0,0,0] op_sel_hi:[1,0,1] neg_hi:[0,0,1]
	v_pk_mul_f32 v[250:251], v[6:7], v[240:241] op_sel:[1,1] op_sel_hi:[0,1]
	v_pk_fma_f32 v[6:7], v[6:7], v[240:241], v[250:251] op_sel:[0,0,0] op_sel_hi:[1,0,1] neg_hi:[0,0,1]
	v_pk_add_f32 v[242:243], v[0:1], v[4:5]
	v_pk_add_f32 v[244:245], v[0:1], v[4:5] neg_lo:[0,1] neg_hi:[0,1]
	v_pk_add_f32 v[246:247], v[2:3], v[6:7]
	v_pk_add_f32 v[248:249], v[2:3], v[6:7] neg_lo:[0,1] neg_hi:[0,1]
	v_pk_add_f32 v[0:1], v[242:243], v[246:247]
	v_pk_add_f32 v[2:3], v[244:245], v[248:249] op_sel:[0,1] op_sel_hi:[1,0] neg_lo:[0,1]
	v_pk_add_f32 v[4:5], v[242:243], v[246:247] neg_lo:[0,1] neg_hi:[0,1]
	v_pk_add_f32 v[6:7], v[244:245], v[248:249] op_sel:[0,1] op_sel_hi:[1,0] neg_hi:[0,1]
	s_waitcnt lgkmcnt(8)
	v_pk_mul_f32 v[250:251], v[12:13], v[238:239] op_sel:[1,1] op_sel_hi:[0,1]
	v_pk_fma_f32 v[12:13], v[12:13], v[238:239], v[250:251] op_sel:[0,0,0] op_sel_hi:[1,0,1] neg_hi:[0,0,1]
	v_pk_mul_f32 v[250:251], v[10:11], v[236:237] op_sel:[1,1] op_sel_hi:[0,1]
	v_pk_fma_f32 v[10:11], v[10:11], v[236:237], v[250:251] op_sel:[0,0,0] op_sel_hi:[1,0,1] neg_hi:[0,0,1]
	v_pk_mul_f32 v[250:251], v[14:15], v[240:241] op_sel:[1,1] op_sel_hi:[0,1]
	v_pk_fma_f32 v[14:15], v[14:15], v[240:241], v[250:251] op_sel:[0,0,0] op_sel_hi:[1,0,1] neg_hi:[0,0,1]
	v_pk_add_f32 v[242:243], v[8:9], v[12:13]
	v_pk_add_f32 v[244:245], v[8:9], v[12:13] neg_lo:[0,1] neg_hi:[0,1]
	v_pk_add_f32 v[246:247], v[10:11], v[14:15]
	v_pk_add_f32 v[248:249], v[10:11], v[14:15] neg_lo:[0,1] neg_hi:[0,1]
	v_pk_add_f32 v[8:9], v[242:243], v[246:247]
	v_pk_add_f32 v[10:11], v[244:245], v[248:249] op_sel:[0,1] op_sel_hi:[1,0] neg_lo:[0,1]
	v_pk_add_f32 v[12:13], v[242:243], v[246:247] neg_lo:[0,1] neg_hi:[0,1]
	v_pk_add_f32 v[14:15], v[244:245], v[248:249] op_sel:[0,1] op_sel_hi:[1,0] neg_hi:[0,1]
	s_waitcnt lgkmcnt(4)
	v_pk_mul_f32 v[250:251], v[20:21], v[238:239] op_sel:[1,1] op_sel_hi:[0,1]
	v_pk_fma_f32 v[20:21], v[20:21], v[238:239], v[250:251] op_sel:[0,0,0] op_sel_hi:[1,0,1] neg_hi:[0,0,1]
	v_pk_mul_f32 v[250:251], v[18:19], v[236:237] op_sel:[1,1] op_sel_hi:[0,1]
	v_pk_fma_f32 v[18:19], v[18:19], v[236:237], v[250:251] op_sel:[0,0,0] op_sel_hi:[1,0,1] neg_hi:[0,0,1]
	v_pk_mul_f32 v[250:251], v[22:23], v[240:241] op_sel:[1,1] op_sel_hi:[0,1]
	v_pk_fma_f32 v[22:23], v[22:23], v[240:241], v[250:251] op_sel:[0,0,0] op_sel_hi:[1,0,1] neg_hi:[0,0,1]
	v_pk_add_f32 v[242:243], v[16:17], v[20:21]
	v_pk_add_f32 v[244:245], v[16:17], v[20:21] neg_lo:[0,1] neg_hi:[0,1]
	v_pk_add_f32 v[246:247], v[18:19], v[22:23]
	v_pk_add_f32 v[248:249], v[18:19], v[22:23] neg_lo:[0,1] neg_hi:[0,1]
	v_pk_add_f32 v[16:17], v[242:243], v[246:247]
	v_pk_add_f32 v[18:19], v[244:245], v[248:249] op_sel:[0,1] op_sel_hi:[1,0] neg_lo:[0,1]
	v_pk_add_f32 v[20:21], v[242:243], v[246:247] neg_lo:[0,1] neg_hi:[0,1]
	v_pk_add_f32 v[22:23], v[244:245], v[248:249] op_sel:[0,1] op_sel_hi:[1,0] neg_hi:[0,1]
	s_waitcnt lgkmcnt(0)
; HD float2 cmul(float2 a, float2 b){ return make_float2(a.x*b.x - a.y*b.y, a.x*b.y + a.y*b.x); }
; HD float2 cmulc(float2 a, float2 b){ return make_float2(a.x*b.x + a.y*b.y, a.y*b.x - a.x*b.y); }
; template<bool INV, bool NOTW>
; HD void bf4c(float2* Z, int i0, int i1, int i2, int i3, float2 w1, float2 w2, float2 w3){
;   float2 a0=Z[i0], a1=Z[i1], a2=Z[i2], a3=Z[i3];
;   if (INV && !NOTW){ a1=cmulc(a1,w1); a2=cmulc(a2,w2); a3=cmulc(a3,w3); }
;   float2 s02=make_float2(a0.x+a2.x,a0.y+a2.y), d02=make_float2(a0.x-a2.x,a0.y-a2.y);
;   float2 s13=make_float2(a1.x+a3.x,a1.y+a3.y), d13=make_float2(a1.x-a3.x,a1.y-a3.y);
;   float2 y0=make_float2(s02.x+s13.x,s02.y+s13.y), y2=make_float2(s02.x-s13.x,s02.y-s13.y);
;   float2 ym=make_float2(d02.x+d13.y,d02.y-d13.x);
;   float2 yp=make_float2(d02.x-d13.y,d02.y+d13.x);
;   float2 y1, y3;
;   if (INV){ y1=yp; y3=ym; } else if (NOTW){ y1=ym; y3=yp; } else { y1=cmul(ym,w1); y2=cmul(y2,w2); y3=cmul(yp,w3); }
;   Z[i0]=y0; Z[i1]=y1; Z[i2]=y2; Z[i3]=y3;
; }
; HD int rev4_14(int p){ unsigned r = __brev((unsigned)p) >> 18; return (int)(((r & 0x2AAAu) >> 1) | ((r & 0x1555u) << 1)); }
; template<bool INV, int LQ, bool BARRIER=true>
; HD void fft_pass(float2* Z, const float2* twA, const float2* twB, int tid){
;   constexpr int q=1<<LQ; constexpr int tws=4096>>LQ;
;   if (LQ==12){
;     _Pragma("unroll 2") for (int i=0;i<8;++i){ int t=tid+512*i; int k=t;
;       float2 w1=cmul(twA[k>>6],twB[k&63]), w2=cmul(w1,w1), w3=cmul(w2,w1);
;       bf4c<INV,false>(Z,t,t+q,t+2*q,t+3*q,w1,w2,w3); }
;   } else if (LQ==10){
;     _Pragma("unroll") for (int e=0;e<2;++e){ int j=tid+512*e; int k=j*tws;
;       float2 w1=cmul(twA[k>>6],twB[k&63]), w2=cmul(w1,w1), w3=cmul(w2,w1);
;       _Pragma("unroll") for (int ip=0;ip<4;++ip){ int base=ip*4096+j; bf4c<INV,false>(Z,base,base+q,base+2*q,base+3*q,w1,w2,w3); } }
;   } else {
;     int j=tid&(q-1); int base0=((tid>>LQ)<<(LQ+2))+j;
;     float2 w1=make_float2(1.f,0.f), w2=w1, w3=w1;
;     if (LQ>0){ int k=j*tws; w1=cmul(twA[k>>6],twB[k&63]); w2=cmul(w1,w1); w3=cmul(w2,w1); }
;     _Pragma("unroll") for (int i=0;i<8;++i){ int base=base0+i*2048; bf4c<INV,(LQ==0)>(Z,base,base+q,base+2*q,base+3*q,w1,w2,w3); }
;   }
;   if (BARRIER) __syncthreads(); else asm volatile("s_waitcnt lgkmcnt(0)" ::: "memory");
; }
	v_pk_mul_f32 v[250:251], v[28:29], v[238:239] op_sel:[1,1] op_sel_hi:[0,1]
	v_pk_fma_f32 v[28:29], v[28:29], v[238:239], v[250:251] op_sel:[0,0,0] op_sel_hi:[1,0,1] neg_hi:[0,0,1]
	v_pk_mul_f32 v[250:251], v[26:27], v[236:237] op_sel:[1,1] op_sel_hi:[0,1]
	v_pk_fma_f32 v[26:27], v[26:27], v[236:237], v[250:251] op_sel:[0,0,0] op_sel_hi:[1,0,1] neg_hi:[0,0,1]
	v_pk_mul_f32 v[250:251], v[30:31], v[240:241] op_sel:[1,1] op_sel_hi:[0,1]
	v_pk_fma_f32 v[30:31], v[30:31], v[240:241], v[250:251] op_sel:[0,0,0] op_sel_hi:[1,0,1] neg_hi:[0,0,1]
	v_pk_add_f32 v[242:243], v[24:25], v[28:29]
	v_pk_add_f32 v[244:245], v[24:25], v[28:29] neg_lo:[0,1] neg_hi:[0,1]
	v_pk_add_f32 v[246:247], v[26:27], v[30:31]
	v_pk_add_f32 v[248:249], v[26:27], v[30:31] neg_lo:[0,1] neg_hi:[0,1]
	v_pk_add_f32 v[24:25], v[242:243], v[246:247]
	v_pk_add_f32 v[26:27], v[244:245], v[248:249] op_sel:[0,1] op_sel_hi:[1,0] neg_lo:[0,1]
	v_pk_add_f32 v[28:29], v[242:243], v[246:247] neg_lo:[0,1] neg_hi:[0,1]
	v_pk_add_f32 v[30:31], v[244:245], v[248:249] op_sel:[0,1] op_sel_hi:[1,0] neg_hi:[0,1]
	v_pk_mul_f32 v[250:251], v[16:17], v[82:83] op_sel:[1,1] op_sel_hi:[0,1]
	v_pk_fma_f32 v[16:17], v[16:17], v[82:83], v[250:251] op_sel:[0,0,0] op_sel_hi:[1,0,1] neg_hi:[0,0,1]
	v_pk_mul_f32 v[250:251], v[8:9], v[80:81] op_sel:[1,1] op_sel_hi:[0,1]
	v_pk_fma_f32 v[8:9], v[8:9], v[80:81], v[250:251] op_sel:[0,0,0] op_sel_hi:[1,0,1] neg_hi:[0,0,1]
	v_pk_mul_f32 v[250:251], v[24:25], v[84:85] op_sel:[1,1] op_sel_hi:[0,1]
	v_pk_fma_f32 v[24:25], v[24:25], v[84:85], v[250:251] op_sel:[0,0,0] op_sel_hi:[1,0,1] neg_hi:[0,0,1]
	v_pk_add_f32 v[242:243], v[0:1], v[16:17]
	v_pk_add_f32 v[244:245], v[0:1], v[16:17] neg_lo:[0,1] neg_hi:[0,1]
	v_pk_add_f32 v[246:247], v[8:9], v[24:25]
	v_pk_add_f32 v[248:249], v[8:9], v[24:25] neg_lo:[0,1] neg_hi:[0,1]
	v_pk_add_f32 v[0:1], v[242:243], v[246:247]
	ds_write_b64 v226, v[0:1] offset:0
	v_pk_add_f32 v[8:9], v[244:245], v[248:249] op_sel:[0,1] op_sel_hi:[1,0] neg_lo:[0,1]
	ds_write_b64 v226, v[8:9] offset:512
	v_pk_add_f32 v[16:17], v[242:243], v[246:247] neg_lo:[0,1] neg_hi:[0,1]
	ds_write_b64 v226, v[16:17] offset:1024
	v_pk_add_f32 v[24:25], v[244:245], v[248:249] op_sel:[0,1] op_sel_hi:[1,0] neg_hi:[0,1]
	ds_write_b64 v226, v[24:25] offset:1536
	v_pk_mul_f32 v[250:251], v[18:19], v[224:225] op_sel:[1,1] op_sel_hi:[1,0] neg_lo:[0,0] neg_hi:[0,0]
	v_pk_fma_f32 v[18:19], v[18:19], v[224:225], v[250:251] op_sel:[0,0,0] op_sel_hi:[0,1,1] neg_lo:[0,0,1] neg_hi:[0,0,0]
	v_pk_mul_f32 v[250:251], v[18:19], v[82:83] op_sel:[1,1] op_sel_hi:[0,1]
	v_pk_fma_f32 v[18:19], v[18:19], v[82:83], v[250:251] op_sel:[0,0,0] op_sel_hi:[1,0,1] neg_hi:[0,0,1]
	v_pk_mul_f32 v[250:251], v[10:11], v[222:223] op_sel:[1,1] op_sel_hi:[1,0] neg_lo:[0,0] neg_hi:[0,0]
	v_pk_fma_f32 v[10:11], v[10:11], v[222:223], v[250:251] op_sel:[0,0,0] op_sel_hi:[0,1,1] neg_lo:[0,0,1] neg_hi:[0,0,0]
	v_pk_mul_f32 v[250:251], v[10:11], v[80:81] op_sel:[1,1] op_sel_hi:[0,1]
	v_pk_fma_f32 v[10:11], v[10:11], v[80:81], v[250:251] op_sel:[0,0,0] op_sel_hi:[1,0,1] neg_hi:[0,0,1]
	v_pk_mul_f32 v[250:251], v[26:27], v[222:223] op_sel:[1,0] op_sel_hi:[1,1] neg_lo:[0,0] neg_hi:[0,0]
	v_pk_fma_f32 v[26:27], v[26:27], v[222:223], v[250:251] op_sel:[0,1,0] op_sel_hi:[0,0,1] neg_lo:[0,0,1] neg_hi:[0,0,0]
	v_pk_mul_f32 v[250:251], v[26:27], v[84:85] op_sel:[1,1] op_sel_hi:[0,1]
	v_pk_fma_f32 v[26:27], v[26:27], v[84:85], v[250:251] op_sel:[0,0,0] op_sel_hi:[1,0,1] neg_hi:[0,0,1]
	v_pk_add_f32 v[242:243], v[2:3], v[18:19]
	v_pk_add_f32 v[244:245], v[2:3], v[18:19] neg_lo:[0,1] neg_hi:[0,1]
	v_pk_add_f32 v[246:247], v[10:11], v[26:27]
	v_pk_add_f32 v[248:249], v[10:11], v[26:27] neg_lo:[0,1] neg_hi:[0,1]
	v_pk_add_f32 v[2:3], v[242:243], v[246:247]
	ds_write_b64 v226, v[2:3] offset:128
	v_pk_add_f32 v[10:11], v[244:245], v[248:249] op_sel:[0,1] op_sel_hi:[1,0] neg_lo:[0,1]
	ds_write_b64 v226, v[10:11] offset:640
	v_pk_add_f32 v[18:19], v[242:243], v[246:247] neg_lo:[0,1] neg_hi:[0,1]
	ds_write_b64 v226, v[18:19] offset:1152
	v_pk_add_f32 v[26:27], v[244:245], v[248:249] op_sel:[0,1] op_sel_hi:[1,0] neg_hi:[0,1]
	ds_write_b64 v226, v[26:27] offset:1664
	v_pk_add_f32 v[20:21], v[20:21], 0 op_sel:[1,0] op_sel_hi:[0,0] neg_lo:[1,0]
	v_pk_mul_f32 v[250:251], v[20:21], v[82:83] op_sel:[1,1] op_sel_hi:[0,1]
	v_pk_fma_f32 v[20:21], v[20:21], v[82:83], v[250:251] op_sel:[0,0,0] op_sel_hi:[1,0,1] neg_hi:[0,0,1]
	v_pk_mul_f32 v[250:251], v[12:13], v[224:225] op_sel:[1,1] op_sel_hi:[1,0] neg_lo:[0,0] neg_hi:[0,0]
	v_pk_fma_f32 v[12:13], v[12:13], v[224:225], v[250:251] op_sel:[0,0,0] op_sel_hi:[0,1,1] neg_lo:[0,0,1] neg_hi:[0,0,0]
	v_pk_mul_f32 v[250:251], v[12:13], v[80:81] op_sel:[1,1] op_sel_hi:[0,1]
	v_pk_fma_f32 v[12:13], v[12:13], v[80:81], v[250:251] op_sel:[0,0,0] op_sel_hi:[1,0,1] neg_hi:[0,0,1]
	v_pk_mul_f32 v[250:251], v[28:29], v[224:225] op_sel:[1,1] op_sel_hi:[1,0] neg_lo:[0,0] neg_hi:[0,1]
	v_pk_fma_f32 v[28:29], v[28:29], v[224:225], v[250:251] op_sel:[0,0,0] op_sel_hi:[0,1,1] neg_lo:[0,1,1] neg_hi:[0,0,0]
	v_pk_mul_f32 v[250:251], v[28:29], v[84:85] op_sel:[1,1] op_sel_hi:[0,1]
	v_pk_fma_f32 v[28:29], v[28:29], v[84:85], v[250:251] op_sel:[0,0,0] op_sel_hi:[1,0,1] neg_hi:[0,0,1]
	v_pk_add_f32 v[242:243], v[4:5], v[20:21]
	v_pk_add_f32 v[244:245], v[4:5], v[20:21] neg_lo:[0,1] neg_hi:[0,1]
	v_pk_add_f32 v[246:247], v[12:13], v[28:29]
	v_pk_add_f32 v[248:249], v[12:13], v[28:29] neg_lo:[0,1] neg_hi:[0,1]
	v_pk_add_f32 v[4:5], v[242:243], v[246:247]
	ds_write_b64 v226, v[4:5] offset:256
	v_pk_add_f32 v[12:13], v[244:245], v[248:249] op_sel:[0,1] op_sel_hi:[1,0] neg_lo:[0,1]
	ds_write_b64 v226, v[12:13] offset:768
; HD float2 cmul(float2 a, float2 b){ return make_float2(a.x*b.x - a.y*b.y, a.x*b.y + a.y*b.x); }
; HD float2 cmulc(float2 a, float2 b){ return make_float2(a.x*b.x + a.y*b.y, a.y*b.x - a.x*b.y); }
; template<bool INV, bool NOTW>
; HD void bf4c(float2* Z, int i0, int i1, int i2, int i3, float2 w1, float2 w2, float2 w3){
;   float2 a0=Z[i0], a1=Z[i1], a2=Z[i2], a3=Z[i3];
;   if (INV && !NOTW){ a1=cmulc(a1,w1); a2=cmulc(a2,w2); a3=cmulc(a3,w3); }
;   float2 s02=make_float2(a0.x+a2.x,a0.y+a2.y), d02=make_float2(a0.x-a2.x,a0.y-a2.y);
;   float2 s13=make_float2(a1.x+a3.x,a1.y+a3.y), d13=make_float2(a1.x-a3.x,a1.y-a3.y);
;   float2 y0=make_float2(s02.x+s13.x,s02.y+s13.y), y2=make_float2(s02.x-s13.x,s02.y-s13.y);
;   float2 ym=make_float2(d02.x+d13.y,d02.y-d13.x);
;   float2 yp=make_float2(d02.x-d13.y,d02.y+d13.x);
;   float2 y1, y3;
;   if (INV){ y1=yp; y3=ym; } else if (NOTW){ y1=ym; y3=yp; } else { y1=cmul(ym,w1); y2=cmul(y2,w2); y3=cmul(yp,w3); }
;   Z[i0]=y0; Z[i1]=y1; Z[i2]=y2; Z[i3]=y3;
; }
; HD int rev4_14(int p){ unsigned r = __brev((unsigned)p) >> 18; return (int)(((r & 0x2AAAu) >> 1) | ((r & 0x1555u) << 1)); }
; template<bool INV, int LQ, bool BARRIER=true>
; HD void fft_pass(float2* Z, const float2* twA, const float2* twB, int tid){
;   constexpr int q=1<<LQ; constexpr int tws=4096>>LQ;
;   if (LQ==12){
;     _Pragma("unroll 2") for (int i=0;i<8;++i){ int t=tid+512*i; int k=t;
;       float2 w1=cmul(twA[k>>6],twB[k&63]), w2=cmul(w1,w1), w3=cmul(w2,w1);
;       bf4c<INV,false>(Z,t,t+q,t+2*q,t+3*q,w1,w2,w3); }
;   } else if (LQ==10){
;     _Pragma("unroll") for (int e=0;e<2;++e){ int j=tid+512*e; int k=j*tws;
;       float2 w1=cmul(twA[k>>6],twB[k&63]), w2=cmul(w1,w1), w3=cmul(w2,w1);
;       _Pragma("unroll") for (int ip=0;ip<4;++ip){ int base=ip*4096+j; bf4c<INV,false>(Z,base,base+q,base+2*q,base+3*q,w1,w2,w3); } }
;   } else {
;     int j=tid&(q-1); int base0=((tid>>LQ)<<(LQ+2))+j;
;     float2 w1=make_float2(1.f,0.f), w2=w1, w3=w1;
;     if (LQ>0){ int k=j*tws; w1=cmul(twA[k>>6],twB[k&63]); w2=cmul(w1,w1); w3=cmul(w2,w1); }
;     _Pragma("unroll") for (int i=0;i<8;++i){ int base=base0+i*2048; bf4c<INV,(LQ==0)>(Z,base,base+q,base+2*q,base+3*q,w1,w2,w3); }
;   }
;   if (BARRIER) __syncthreads(); else asm volatile("s_waitcnt lgkmcnt(0)" ::: "memory");
; }
	v_pk_add_f32 v[20:21], v[242:243], v[246:247] neg_lo:[0,1] neg_hi:[0,1]
	ds_write_b64 v226, v[20:21] offset:1280
	v_pk_add_f32 v[28:29], v[244:245], v[248:249] op_sel:[0,1] op_sel_hi:[1,0] neg_hi:[0,1]
	ds_write_b64 v226, v[28:29] offset:1792
	v_pk_mul_f32 v[250:251], v[22:23], v[224:225] op_sel:[1,1] op_sel_hi:[1,0] neg_lo:[0,0] neg_hi:[0,1]
	v_pk_fma_f32 v[22:23], v[22:23], v[224:225], v[250:251] op_sel:[0,0,0] op_sel_hi:[0,1,1] neg_lo:[0,1,1] neg_hi:[0,0,0]
	v_pk_mul_f32 v[250:251], v[22:23], v[82:83] op_sel:[1,1] op_sel_hi:[0,1]
	v_pk_fma_f32 v[22:23], v[22:23], v[82:83], v[250:251] op_sel:[0,0,0] op_sel_hi:[1,0,1] neg_hi:[0,0,1]
	v_pk_mul_f32 v[250:251], v[14:15], v[222:223] op_sel:[1,0] op_sel_hi:[1,1] neg_lo:[0,0] neg_hi:[0,0]
	v_pk_fma_f32 v[14:15], v[14:15], v[222:223], v[250:251] op_sel:[0,1,0] op_sel_hi:[0,0,1] neg_lo:[0,0,1] neg_hi:[0,0,0]
	v_pk_mul_f32 v[250:251], v[14:15], v[80:81] op_sel:[1,1] op_sel_hi:[0,1]
	v_pk_fma_f32 v[14:15], v[14:15], v[80:81], v[250:251] op_sel:[0,0,0] op_sel_hi:[1,0,1] neg_hi:[0,0,1]
	v_pk_mul_f32 v[250:251], v[30:31], v[222:223] op_sel:[1,1] op_sel_hi:[1,0] neg_lo:[0,1] neg_hi:[0,1]
	v_pk_fma_f32 v[30:31], v[30:31], v[222:223], v[250:251] op_sel:[0,0,0] op_sel_hi:[0,1,1] neg_lo:[0,1,1] neg_hi:[0,1,0]
	v_pk_mul_f32 v[250:251], v[30:31], v[84:85] op_sel:[1,1] op_sel_hi:[0,1]
	v_pk_fma_f32 v[30:31], v[30:31], v[84:85], v[250:251] op_sel:[0,0,0] op_sel_hi:[1,0,1] neg_hi:[0,0,1]
	v_pk_add_f32 v[242:243], v[6:7], v[22:23]
	v_pk_add_f32 v[244:245], v[6:7], v[22:23] neg_lo:[0,1] neg_hi:[0,1]
	v_pk_add_f32 v[246:247], v[14:15], v[30:31]
	v_pk_add_f32 v[248:249], v[14:15], v[30:31] neg_lo:[0,1] neg_hi:[0,1]
	v_pk_add_f32 v[6:7], v[242:243], v[246:247]
	ds_write_b64 v226, v[6:7] offset:384
	v_pk_add_f32 v[14:15], v[244:245], v[248:249] op_sel:[0,1] op_sel_hi:[1,0] neg_lo:[0,1]
	ds_write_b64 v226, v[14:15] offset:896
	v_pk_add_f32 v[22:23], v[242:243], v[246:247] neg_lo:[0,1] neg_hi:[0,1]
	ds_write_b64 v226, v[22:23] offset:1408
	v_pk_add_f32 v[30:31], v[244:245], v[248:249] op_sel:[0,1] op_sel_hi:[1,0] neg_hi:[0,1]
	ds_write_b64 v226, v[30:31] offset:1920
	ds_read_b64 v[0:1], v227 offset:0
	ds_read_b64 v[2:3], v227 offset:128
	ds_read_b64 v[4:5], v227 offset:256
	ds_read_b64 v[6:7], v227 offset:384
	ds_read_b64 v[8:9], v227 offset:512
	ds_read_b64 v[10:11], v227 offset:640
	ds_read_b64 v[12:13], v227 offset:768
	ds_read_b64 v[14:15], v227 offset:896
	ds_read_b64 v[16:17], v227 offset:1024
	ds_read_b64 v[18:19], v227 offset:1152
	ds_read_b64 v[20:21], v227 offset:1280
	ds_read_b64 v[22:23], v227 offset:1408
	ds_read_b64 v[24:25], v227 offset:1536
	ds_read_b64 v[26:27], v227 offset:1664
	ds_read_b64 v[28:29], v227 offset:1792
	ds_read_b64 v[30:31], v227 offset:1920
	s_waitcnt lgkmcnt(12)
	v_pk_mul_f32 v[250:251], v[4:5], v[238:239] op_sel:[1,1] op_sel_hi:[0,1]
	v_pk_fma_f32 v[4:5], v[4:5], v[238:239], v[250:251] op_sel:[0,0,0] op_sel_hi:[1,0,1] neg_hi:[0,0,1]
	v_pk_mul_f32 v[250:251], v[2:3], v[236:237] op_sel:[1,1] op_sel_hi:[0,1]
	v_pk_fma_f32 v[2:3], v[2:3], v[236:237], v[250:251] op_sel:[0,0,0] op_sel_hi:[1,0,1] neg_hi:[0,0,1]
	v_pk_mul_f32 v[250:251], v[6:7], v[240:241] op_sel:[1,1] op_sel_hi:[0,1]
	v_pk_fma_f32 v[6:7], v[6:7], v[240:241], v[250:251] op_sel:[0,0,0] op_sel_hi:[1,0,1] neg_hi:[0,0,1]
	v_pk_add_f32 v[242:243], v[0:1], v[4:5]
	v_pk_add_f32 v[244:245], v[0:1], v[4:5] neg_lo:[0,1] neg_hi:[0,1]
	v_pk_add_f32 v[246:247], v[2:3], v[6:7]
	v_pk_add_f32 v[248:249], v[2:3], v[6:7] neg_lo:[0,1] neg_hi:[0,1]
	v_pk_add_f32 v[0:1], v[242:243], v[246:247]
	v_pk_add_f32 v[2:3], v[244:245], v[248:249] op_sel:[0,1] op_sel_hi:[1,0] neg_lo:[0,1]
	v_pk_add_f32 v[4:5], v[242:243], v[246:247] neg_lo:[0,1] neg_hi:[0,1]
	v_pk_add_f32 v[6:7], v[244:245], v[248:249] op_sel:[0,1] op_sel_hi:[1,0] neg_hi:[0,1]
	s_waitcnt lgkmcnt(8)
	v_pk_mul_f32 v[250:251], v[12:13], v[238:239] op_sel:[1,1] op_sel_hi:[0,1]
	v_pk_fma_f32 v[12:13], v[12:13], v[238:239], v[250:251] op_sel:[0,0,0] op_sel_hi:[1,0,1] neg_hi:[0,0,1]
	v_pk_mul_f32 v[250:251], v[10:11], v[236:237] op_sel:[1,1] op_sel_hi:[0,1]
	v_pk_fma_f32 v[10:11], v[10:11], v[236:237], v[250:251] op_sel:[0,0,0] op_sel_hi:[1,0,1] neg_hi:[0,0,1]
	v_pk_mul_f32 v[250:251], v[14:15], v[240:241] op_sel:[1,1] op_sel_hi:[0,1]
	v_pk_fma_f32 v[14:15], v[14:15], v[240:241], v[250:251] op_sel:[0,0,0] op_sel_hi:[1,0,1] neg_hi:[0,0,1]
	v_pk_add_f32 v[242:243], v[8:9], v[12:13]
	v_pk_add_f32 v[244:245], v[8:9], v[12:13] neg_lo:[0,1] neg_hi:[0,1]
	v_pk_add_f32 v[246:247], v[10:11], v[14:15]
	v_pk_add_f32 v[248:249], v[10:11], v[14:15] neg_lo:[0,1] neg_hi:[0,1]
	v_pk_add_f32 v[8:9], v[242:243], v[246:247]
	v_pk_add_f32 v[10:11], v[244:245], v[248:249] op_sel:[0,1] op_sel_hi:[1,0] neg_lo:[0,1]
	v_pk_add_f32 v[12:13], v[242:243], v[246:247] neg_lo:[0,1] neg_hi:[0,1]
	v_pk_add_f32 v[14:15], v[244:245], v[248:249] op_sel:[0,1] op_sel_hi:[1,0] neg_hi:[0,1]
	s_waitcnt lgkmcnt(4)
	v_pk_mul_f32 v[250:251], v[20:21], v[238:239] op_sel:[1,1] op_sel_hi:[0,1]
	v_pk_fma_f32 v[20:21], v[20:21], v[238:239], v[250:251] op_sel:[0,0,0] op_sel_hi:[1,0,1] neg_hi:[0,0,1]
	v_pk_mul_f32 v[250:251], v[18:19], v[236:237] op_sel:[1,1] op_sel_hi:[0,1]
	v_pk_fma_f32 v[18:19], v[18:19], v[236:237], v[250:251] op_sel:[0,0,0] op_sel_hi:[1,0,1] neg_hi:[0,0,1]
	v_pk_mul_f32 v[250:251], v[22:23], v[240:241] op_sel:[1,1] op_sel_hi:[0,1]
	v_pk_fma_f32 v[22:23], v[22:23], v[240:241], v[250:251] op_sel:[0,0,0] op_sel_hi:[1,0,1] neg_hi:[0,0,1]
	v_pk_add_f32 v[242:243], v[16:17], v[20:21]
	v_pk_add_f32 v[244:245], v[16:17], v[20:21] neg_lo:[0,1] neg_hi:[0,1]
	v_pk_add_f32 v[246:247], v[18:19], v[22:23]
	v_pk_add_f32 v[248:249], v[18:19], v[22:23] neg_lo:[0,1] neg_hi:[0,1]
	v_pk_add_f32 v[16:17], v[242:243], v[246:247]
	v_pk_add_f32 v[18:19], v[244:245], v[248:249] op_sel:[0,1] op_sel_hi:[1,0] neg_lo:[0,1]
	v_pk_add_f32 v[20:21], v[242:243], v[246:247] neg_lo:[0,1] neg_hi:[0,1]
	v_pk_add_f32 v[22:23], v[244:245], v[248:249] op_sel:[0,1] op_sel_hi:[1,0] neg_hi:[0,1]
	s_waitcnt lgkmcnt(0)
; HD float2 cmul(float2 a, float2 b){ return make_float2(a.x*b.x - a.y*b.y, a.x*b.y + a.y*b.x); }
; HD float2 cmulc(float2 a, float2 b){ return make_float2(a.x*b.x + a.y*b.y, a.y*b.x - a.x*b.y); }
; template<bool INV, bool NOTW>
; HD void bf4c(float2* Z, int i0, int i1, int i2, int i3, float2 w1, float2 w2, float2 w3){
;   float2 a0=Z[i0], a1=Z[i1], a2=Z[i2], a3=Z[i3];
;   if (INV && !NOTW){ a1=cmulc(a1,w1); a2=cmulc(a2,w2); a3=cmulc(a3,w3); }
;   float2 s02=make_float2(a0.x+a2.x,a0.y+a2.y), d02=make_float2(a0.x-a2.x,a0.y-a2.y);
;   float2 s13=make_float2(a1.x+a3.x,a1.y+a3.y), d13=make_float2(a1.x-a3.x,a1.y-a3.y);
;   float2 y0=make_float2(s02.x+s13.x,s02.y+s13.y), y2=make_float2(s02.x-s13.x,s02.y-s13.y);
;   float2 ym=make_float2(d02.x+d13.y,d02.y-d13.x);
;   float2 yp=make_float2(d02.x-d13.y,d02.y+d13.x);
;   float2 y1, y3;
;   if (INV){ y1=yp; y3=ym; } else if (NOTW){ y1=ym; y3=yp; } else { y1=cmul(ym,w1); y2=cmul(y2,w2); y3=cmul(yp,w3); }
;   Z[i0]=y0; Z[i1]=y1; Z[i2]=y2; Z[i3]=y3;
; }
; HD int rev4_14(int p){ unsigned r = __brev((unsigned)p) >> 18; return (int)(((r & 0x2AAAu) >> 1) | ((r & 0x1555u) << 1)); }
; template<bool INV, int LQ, bool BARRIER=true>
; HD void fft_pass(float2* Z, const float2* twA, const float2* twB, int tid){
;   constexpr int q=1<<LQ; constexpr int tws=4096>>LQ;
;   if (LQ==12){
;     _Pragma("unroll 2") for (int i=0;i<8;++i){ int t=tid+512*i; int k=t;
;       float2 w1=cmul(twA[k>>6],twB[k&63]), w2=cmul(w1,w1), w3=cmul(w2,w1);
;       bf4c<INV,false>(Z,t,t+q,t+2*q,t+3*q,w1,w2,w3); }
;   } else if (LQ==10){
;     _Pragma("unroll") for (int e=0;e<2;++e){ int j=tid+512*e; int k=j*tws;
;       float2 w1=cmul(twA[k>>6],twB[k&63]), w2=cmul(w1,w1), w3=cmul(w2,w1);
;       _Pragma("unroll") for (int ip=0;ip<4;++ip){ int base=ip*4096+j; bf4c<INV,false>(Z,base,base+q,base+2*q,base+3*q,w1,w2,w3); } }
;   } else {
;     int j=tid&(q-1); int base0=((tid>>LQ)<<(LQ+2))+j;
;     float2 w1=make_float2(1.f,0.f), w2=w1, w3=w1;
;     if (LQ>0){ int k=j*tws; w1=cmul(twA[k>>6],twB[k&63]); w2=cmul(w1,w1); w3=cmul(w2,w1); }
;     _Pragma("unroll") for (int i=0;i<8;++i){ int base=base0+i*2048; bf4c<INV,(LQ==0)>(Z,base,base+q,base+2*q,base+3*q,w1,w2,w3); }
;   }
;   if (BARRIER) __syncthreads(); else asm volatile("s_waitcnt lgkmcnt(0)" ::: "memory");
; }
	v_pk_mul_f32 v[250:251], v[28:29], v[238:239] op_sel:[1,1] op_sel_hi:[0,1]
	v_pk_fma_f32 v[28:29], v[28:29], v[238:239], v[250:251] op_sel:[0,0,0] op_sel_hi:[1,0,1] neg_hi:[0,0,1]
	v_pk_mul_f32 v[250:251], v[26:27], v[236:237] op_sel:[1,1] op_sel_hi:[0,1]
	v_pk_fma_f32 v[26:27], v[26:27], v[236:237], v[250:251] op_sel:[0,0,0] op_sel_hi:[1,0,1] neg_hi:[0,0,1]
	v_pk_mul_f32 v[250:251], v[30:31], v[240:241] op_sel:[1,1] op_sel_hi:[0,1]
	v_pk_fma_f32 v[30:31], v[30:31], v[240:241], v[250:251] op_sel:[0,0,0] op_sel_hi:[1,0,1] neg_hi:[0,0,1]
	v_pk_add_f32 v[242:243], v[24:25], v[28:29]
	v_pk_add_f32 v[244:245], v[24:25], v[28:29] neg_lo:[0,1] neg_hi:[0,1]
	v_pk_add_f32 v[246:247], v[26:27], v[30:31]
	v_pk_add_f32 v[248:249], v[26:27], v[30:31] neg_lo:[0,1] neg_hi:[0,1]
	v_pk_add_f32 v[24:25], v[242:243], v[246:247]
	v_pk_add_f32 v[26:27], v[244:245], v[248:249] op_sel:[0,1] op_sel_hi:[1,0] neg_lo:[0,1]
	v_pk_add_f32 v[28:29], v[242:243], v[246:247] neg_lo:[0,1] neg_hi:[0,1]
	v_pk_add_f32 v[30:31], v[244:245], v[248:249] op_sel:[0,1] op_sel_hi:[1,0] neg_hi:[0,1]
	v_pk_mul_f32 v[250:251], v[16:17], v[82:83] op_sel:[1,1] op_sel_hi:[0,1]
	v_pk_fma_f32 v[16:17], v[16:17], v[82:83], v[250:251] op_sel:[0,0,0] op_sel_hi:[1,0,1] neg_hi:[0,0,1]
	v_pk_mul_f32 v[250:251], v[8:9], v[80:81] op_sel:[1,1] op_sel_hi:[0,1]
	v_pk_fma_f32 v[8:9], v[8:9], v[80:81], v[250:251] op_sel:[0,0,0] op_sel_hi:[1,0,1] neg_hi:[0,0,1]
	v_pk_mul_f32 v[250:251], v[24:25], v[84:85] op_sel:[1,1] op_sel_hi:[0,1]
	v_pk_fma_f32 v[24:25], v[24:25], v[84:85], v[250:251] op_sel:[0,0,0] op_sel_hi:[1,0,1] neg_hi:[0,0,1]
	v_pk_add_f32 v[242:243], v[0:1], v[16:17]
	v_pk_add_f32 v[244:245], v[0:1], v[16:17] neg_lo:[0,1] neg_hi:[0,1]
	v_pk_add_f32 v[246:247], v[8:9], v[24:25]
	v_pk_add_f32 v[248:249], v[8:9], v[24:25] neg_lo:[0,1] neg_hi:[0,1]
	v_pk_add_f32 v[0:1], v[242:243], v[246:247]
	ds_write_b64 v227, v[0:1] offset:0
	v_pk_add_f32 v[8:9], v[244:245], v[248:249] op_sel:[0,1] op_sel_hi:[1,0] neg_lo:[0,1]
	ds_write_b64 v227, v[8:9] offset:512
	v_pk_add_f32 v[16:17], v[242:243], v[246:247] neg_lo:[0,1] neg_hi:[0,1]
	ds_write_b64 v227, v[16:17] offset:1024
	v_pk_add_f32 v[24:25], v[244:245], v[248:249] op_sel:[0,1] op_sel_hi:[1,0] neg_hi:[0,1]
	ds_write_b64 v227, v[24:25] offset:1536
	v_pk_mul_f32 v[250:251], v[18:19], v[224:225] op_sel:[1,1] op_sel_hi:[1,0] neg_lo:[0,0] neg_hi:[0,0]
	v_pk_fma_f32 v[18:19], v[18:19], v[224:225], v[250:251] op_sel:[0,0,0] op_sel_hi:[0,1,1] neg_lo:[0,0,1] neg_hi:[0,0,0]
	v_pk_mul_f32 v[250:251], v[18:19], v[82:83] op_sel:[1,1] op_sel_hi:[0,1]
	v_pk_fma_f32 v[18:19], v[18:19], v[82:83], v[250:251] op_sel:[0,0,0] op_sel_hi:[1,0,1] neg_hi:[0,0,1]
	v_pk_mul_f32 v[250:251], v[10:11], v[222:223] op_sel:[1,1] op_sel_hi:[1,0] neg_lo:[0,0] neg_hi:[0,0]
	v_pk_fma_f32 v[10:11], v[10:11], v[222:223], v[250:251] op_sel:[0,0,0] op_sel_hi:[0,1,1] neg_lo:[0,0,1] neg_hi:[0,0,0]
	v_pk_mul_f32 v[250:251], v[10:11], v[80:81] op_sel:[1,1] op_sel_hi:[0,1]
	v_pk_fma_f32 v[10:11], v[10:11], v[80:81], v[250:251] op_sel:[0,0,0] op_sel_hi:[1,0,1] neg_hi:[0,0,1]
	v_pk_mul_f32 v[250:251], v[26:27], v[222:223] op_sel:[1,0] op_sel_hi:[1,1] neg_lo:[0,0] neg_hi:[0,0]
	v_pk_fma_f32 v[26:27], v[26:27], v[222:223], v[250:251] op_sel:[0,1,0] op_sel_hi:[0,0,1] neg_lo:[0,0,1] neg_hi:[0,0,0]
	v_pk_mul_f32 v[250:251], v[26:27], v[84:85] op_sel:[1,1] op_sel_hi:[0,1]
	v_pk_fma_f32 v[26:27], v[26:27], v[84:85], v[250:251] op_sel:[0,0,0] op_sel_hi:[1,0,1] neg_hi:[0,0,1]
	v_pk_add_f32 v[242:243], v[2:3], v[18:19]
	v_pk_add_f32 v[244:245], v[2:3], v[18:19] neg_lo:[0,1] neg_hi:[0,1]
	v_pk_add_f32 v[246:247], v[10:11], v[26:27]
	v_pk_add_f32 v[248:249], v[10:11], v[26:27] neg_lo:[0,1] neg_hi:[0,1]
	v_pk_add_f32 v[2:3], v[242:243], v[246:247]
	ds_write_b64 v227, v[2:3] offset:128
	v_pk_add_f32 v[10:11], v[244:245], v[248:249] op_sel:[0,1] op_sel_hi:[1,0] neg_lo:[0,1]
	ds_write_b64 v227, v[10:11] offset:640
	v_pk_add_f32 v[18:19], v[242:243], v[246:247] neg_lo:[0,1] neg_hi:[0,1]
	ds_write_b64 v227, v[18:19] offset:1152
	v_pk_add_f32 v[26:27], v[244:245], v[248:249] op_sel:[0,1] op_sel_hi:[1,0] neg_hi:[0,1]
	ds_write_b64 v227, v[26:27] offset:1664
	v_pk_add_f32 v[20:21], v[20:21], 0 op_sel:[1,0] op_sel_hi:[0,0] neg_lo:[1,0]
	v_pk_mul_f32 v[250:251], v[20:21], v[82:83] op_sel:[1,1] op_sel_hi:[0,1]
	v_pk_fma_f32 v[20:21], v[20:21], v[82:83], v[250:251] op_sel:[0,0,0] op_sel_hi:[1,0,1] neg_hi:[0,0,1]
	v_pk_mul_f32 v[250:251], v[12:13], v[224:225] op_sel:[1,1] op_sel_hi:[1,0] neg_lo:[0,0] neg_hi:[0,0]
	v_pk_fma_f32 v[12:13], v[12:13], v[224:225], v[250:251] op_sel:[0,0,0] op_sel_hi:[0,1,1] neg_lo:[0,0,1] neg_hi:[0,0,0]
	v_pk_mul_f32 v[250:251], v[12:13], v[80:81] op_sel:[1,1] op_sel_hi:[0,1]
	v_pk_fma_f32 v[12:13], v[12:13], v[80:81], v[250:251] op_sel:[0,0,0] op_sel_hi:[1,0,1] neg_hi:[0,0,1]
	v_pk_mul_f32 v[250:251], v[28:29], v[224:225] op_sel:[1,1] op_sel_hi:[1,0] neg_lo:[0,0] neg_hi:[0,1]
	v_pk_fma_f32 v[28:29], v[28:29], v[224:225], v[250:251] op_sel:[0,0,0] op_sel_hi:[0,1,1] neg_lo:[0,1,1] neg_hi:[0,0,0]
	v_pk_mul_f32 v[250:251], v[28:29], v[84:85] op_sel:[1,1] op_sel_hi:[0,1]
	v_pk_fma_f32 v[28:29], v[28:29], v[84:85], v[250:251] op_sel:[0,0,0] op_sel_hi:[1,0,1] neg_hi:[0,0,1]
	v_pk_add_f32 v[242:243], v[4:5], v[20:21]
	v_pk_add_f32 v[244:245], v[4:5], v[20:21] neg_lo:[0,1] neg_hi:[0,1]
	v_pk_add_f32 v[246:247], v[12:13], v[28:29]
	v_pk_add_f32 v[248:249], v[12:13], v[28:29] neg_lo:[0,1] neg_hi:[0,1]
	v_pk_add_f32 v[4:5], v[242:243], v[246:247]
	ds_write_b64 v227, v[4:5] offset:256
	v_pk_add_f32 v[12:13], v[244:245], v[248:249] op_sel:[0,1] op_sel_hi:[1,0] neg_lo:[0,1]
	ds_write_b64 v227, v[12:13] offset:768
; HD float2 cmul(float2 a, float2 b){ return make_float2(a.x*b.x - a.y*b.y, a.x*b.y + a.y*b.x); }
; HD float2 cmulc(float2 a, float2 b){ return make_float2(a.x*b.x + a.y*b.y, a.y*b.x - a.x*b.y); }
; template<bool INV, bool NOTW>
; HD void bf4c(float2* Z, int i0, int i1, int i2, int i3, float2 w1, float2 w2, float2 w3){
;   float2 a0=Z[i0], a1=Z[i1], a2=Z[i2], a3=Z[i3];
;   if (INV && !NOTW){ a1=cmulc(a1,w1); a2=cmulc(a2,w2); a3=cmulc(a3,w3); }
;   float2 s02=make_float2(a0.x+a2.x,a0.y+a2.y), d02=make_float2(a0.x-a2.x,a0.y-a2.y);
;   float2 s13=make_float2(a1.x+a3.x,a1.y+a3.y), d13=make_float2(a1.x-a3.x,a1.y-a3.y);
;   float2 y0=make_float2(s02.x+s13.x,s02.y+s13.y), y2=make_float2(s02.x-s13.x,s02.y-s13.y);
;   float2 ym=make_float2(d02.x+d13.y,d02.y-d13.x);
;   float2 yp=make_float2(d02.x-d13.y,d02.y+d13.x);
;   float2 y1, y3;
;   if (INV){ y1=yp; y3=ym; } else if (NOTW){ y1=ym; y3=yp; } else { y1=cmul(ym,w1); y2=cmul(y2,w2); y3=cmul(yp,w3); }
;   Z[i0]=y0; Z[i1]=y1; Z[i2]=y2; Z[i3]=y3;
; }
; HD int rev4_14(int p){ unsigned r = __brev((unsigned)p) >> 18; return (int)(((r & 0x2AAAu) >> 1) | ((r & 0x1555u) << 1)); }
; template<bool INV, int LQ, bool BARRIER=true>
; HD void fft_pass(float2* Z, const float2* twA, const float2* twB, int tid){
;   constexpr int q=1<<LQ; constexpr int tws=4096>>LQ;
;   if (LQ==12){
;     _Pragma("unroll 2") for (int i=0;i<8;++i){ int t=tid+512*i; int k=t;
;       float2 w1=cmul(twA[k>>6],twB[k&63]), w2=cmul(w1,w1), w3=cmul(w2,w1);
;       bf4c<INV,false>(Z,t,t+q,t+2*q,t+3*q,w1,w2,w3); }
;   } else if (LQ==10){
;     _Pragma("unroll") for (int e=0;e<2;++e){ int j=tid+512*e; int k=j*tws;
;       float2 w1=cmul(twA[k>>6],twB[k&63]), w2=cmul(w1,w1), w3=cmul(w2,w1);
;       _Pragma("unroll") for (int ip=0;ip<4;++ip){ int base=ip*4096+j; bf4c<INV,false>(Z,base,base+q,base+2*q,base+3*q,w1,w2,w3); } }
;   } else {
;     int j=tid&(q-1); int base0=((tid>>LQ)<<(LQ+2))+j;
;     float2 w1=make_float2(1.f,0.f), w2=w1, w3=w1;
;     if (LQ>0){ int k=j*tws; w1=cmul(twA[k>>6],twB[k&63]); w2=cmul(w1,w1); w3=cmul(w2,w1); }
;     _Pragma("unroll") for (int i=0;i<8;++i){ int base=base0+i*2048; bf4c<INV,(LQ==0)>(Z,base,base+q,base+2*q,base+3*q,w1,w2,w3); }
;   }
;   if (BARRIER) __syncthreads(); else asm volatile("s_waitcnt lgkmcnt(0)" ::: "memory");
; }
	v_pk_add_f32 v[20:21], v[242:243], v[246:247] neg_lo:[0,1] neg_hi:[0,1]
	ds_write_b64 v227, v[20:21] offset:1280
	v_pk_add_f32 v[28:29], v[244:245], v[248:249] op_sel:[0,1] op_sel_hi:[1,0] neg_hi:[0,1]
	ds_write_b64 v227, v[28:29] offset:1792
	v_pk_mul_f32 v[250:251], v[22:23], v[224:225] op_sel:[1,1] op_sel_hi:[1,0] neg_lo:[0,0] neg_hi:[0,1]
	v_pk_fma_f32 v[22:23], v[22:23], v[224:225], v[250:251] op_sel:[0,0,0] op_sel_hi:[0,1,1] neg_lo:[0,1,1] neg_hi:[0,0,0]
	v_pk_mul_f32 v[250:251], v[22:23], v[82:83] op_sel:[1,1] op_sel_hi:[0,1]
	v_pk_fma_f32 v[22:23], v[22:23], v[82:83], v[250:251] op_sel:[0,0,0] op_sel_hi:[1,0,1] neg_hi:[0,0,1]
	v_pk_mul_f32 v[250:251], v[14:15], v[222:223] op_sel:[1,0] op_sel_hi:[1,1] neg_lo:[0,0] neg_hi:[0,0]
	v_pk_fma_f32 v[14:15], v[14:15], v[222:223], v[250:251] op_sel:[0,1,0] op_sel_hi:[0,0,1] neg_lo:[0,0,1] neg_hi:[0,0,0]
	v_pk_mul_f32 v[250:251], v[14:15], v[80:81] op_sel:[1,1] op_sel_hi:[0,1]
	v_pk_fma_f32 v[14:15], v[14:15], v[80:81], v[250:251] op_sel:[0,0,0] op_sel_hi:[1,0,1] neg_hi:[0,0,1]
	v_pk_mul_f32 v[250:251], v[30:31], v[222:223] op_sel:[1,1] op_sel_hi:[1,0] neg_lo:[0,1] neg_hi:[0,1]
	v_pk_fma_f32 v[30:31], v[30:31], v[222:223], v[250:251] op_sel:[0,0,0] op_sel_hi:[0,1,1] neg_lo:[0,1,1] neg_hi:[0,1,0]
	v_pk_mul_f32 v[250:251], v[30:31], v[84:85] op_sel:[1,1] op_sel_hi:[0,1]
	v_pk_fma_f32 v[30:31], v[30:31], v[84:85], v[250:251] op_sel:[0,0,0] op_sel_hi:[1,0,1] neg_hi:[0,0,1]
	v_pk_add_f32 v[242:243], v[6:7], v[22:23]
	v_pk_add_f32 v[244:245], v[6:7], v[22:23] neg_lo:[0,1] neg_hi:[0,1]
	v_pk_add_f32 v[246:247], v[14:15], v[30:31]
	v_pk_add_f32 v[248:249], v[14:15], v[30:31] neg_lo:[0,1] neg_hi:[0,1]
	v_pk_add_f32 v[6:7], v[242:243], v[246:247]
	ds_write_b64 v227, v[6:7] offset:384
	v_pk_add_f32 v[14:15], v[244:245], v[248:249] op_sel:[0,1] op_sel_hi:[1,0] neg_lo:[0,1]
	ds_write_b64 v227, v[14:15] offset:896
	v_pk_add_f32 v[22:23], v[242:243], v[246:247] neg_lo:[0,1] neg_hi:[0,1]
	ds_write_b64 v227, v[22:23] offset:1408
	v_pk_add_f32 v[30:31], v[244:245], v[248:249] op_sel:[0,1] op_sel_hi:[1,0] neg_hi:[0,1]
	ds_write_b64 v227, v[30:31] offset:1920
	s_waitcnt lgkmcnt(0)
	s_barrier
	v_and_b32_e32 v8, 255, v154
	v_lshrrev_b32_e32 v9, 4, v8
	v_lshlrev_b32_e32 v9, 3, v9
	v_add_u32_e32 v9, 0x20800, v9
	v_and_b32_e32 v10, 15, v8
	v_lshlrev_b32_e32 v10, 5, v10
	v_add_u32_e32 v10, 0x20a00, v10
	ds_read_b64 v[0:1], v9
	ds_read_b64 v[2:3], v10
	s_waitcnt lgkmcnt(0)
	v_pk_mul_f32 v[250:251], v[0:1], v[2:3] op_sel:[1,1] op_sel_hi:[1,0]
	v_pk_fma_f32 v[80:81], v[0:1], v[2:3], v[250:251] op_sel:[0,0,0] op_sel_hi:[0,1,1] neg_lo:[0,0,1]
	v_pk_mul_f32 v[250:251], v[80:81], v[80:81] op_sel:[1,1] op_sel_hi:[1,0]
	v_pk_fma_f32 v[82:83], v[80:81], v[80:81], v[250:251] op_sel:[0,0,0] op_sel_hi:[0,1,1] neg_lo:[0,0,1]
	v_pk_mul_f32 v[250:251], v[82:83], v[80:81] op_sel:[1,1] op_sel_hi:[1,0]
	v_pk_fma_f32 v[84:85], v[82:83], v[80:81], v[250:251] op_sel:[0,0,0] op_sel_hi:[0,1,1] neg_lo:[0,0,1]
	v_lshrrev_b32_e32 v9, 2, v8
	v_lshlrev_b32_e32 v9, 3, v9
	v_add_u32_e32 v9, 0x20800, v9
	v_and_b32_e32 v10, 3, v8
	v_lshlrev_b32_e32 v10, 7, v10
	v_add_u32_e32 v10, 0x20a00, v10
	ds_read_b64 v[0:1], v9
	ds_read_b64 v[2:3], v10
	s_waitcnt lgkmcnt(0)
	v_pk_mul_f32 v[250:251], v[0:1], v[2:3] op_sel:[1,1] op_sel_hi:[1,0]
	v_pk_fma_f32 v[236:237], v[0:1], v[2:3], v[250:251] op_sel:[0,0,0] op_sel_hi:[0,1,1] neg_lo:[0,0,1]
	v_pk_mul_f32 v[250:251], v[236:237], v[236:237] op_sel:[1,1] op_sel_hi:[1,0]
	v_pk_fma_f32 v[238:239], v[236:237], v[236:237], v[250:251] op_sel:[0,0,0] op_sel_hi:[0,1,1] neg_lo:[0,0,1]
	v_pk_mul_f32 v[250:251], v[238:239], v[236:237] op_sel:[1,1] op_sel_hi:[1,0]
	v_pk_fma_f32 v[240:241], v[238:239], v[236:237], v[250:251] op_sel:[0,0,0] op_sel_hi:[0,1,1] neg_lo:[0,0,1]
	v_lshrrev_b32_e32 v226, 8, v154
	v_lshlrev_b32_e32 v226, 12, v226
	v_and_b32_e32 v227, 255, v154
	v_add_u32_e32 v226, v226, v227
	v_lshlrev_b32_e32 v226, 3, v226
	v_add_u32_e32 v227, 0x10000, v226
	ds_read_b64 v[0:1], v226 offset:0
	ds_read_b64 v[2:3], v226 offset:2048
	ds_read_b64 v[4:5], v226 offset:4096
	ds_read_b64 v[6:7], v226 offset:6144
	ds_read_b64 v[8:9], v226 offset:8192
	ds_read_b64 v[10:11], v226 offset:10240
	ds_read_b64 v[12:13], v226 offset:12288
	ds_read_b64 v[14:15], v226 offset:14336
	ds_read_b64 v[16:17], v226 offset:16384
	ds_read_b64 v[18:19], v226 offset:18432
	ds_read_b64 v[20:21], v226 offset:20480
	ds_read_b64 v[22:23], v226 offset:22528
	ds_read_b64 v[24:25], v226 offset:24576
	ds_read_b64 v[26:27], v226 offset:26624
	ds_read_b64 v[28:29], v226 offset:28672
	ds_read_b64 v[30:31], v226 offset:30720
	s_waitcnt lgkmcnt(12)
	v_pk_mul_f32 v[250:251], v[4:5], v[238:239] op_sel:[1,1] op_sel_hi:[0,1]
	v_pk_fma_f32 v[4:5], v[4:5], v[238:239], v[250:251] op_sel:[0,0,0] op_sel_hi:[1,0,1] neg_hi:[0,0,1]
	v_pk_mul_f32 v[250:251], v[2:3], v[236:237] op_sel:[1,1] op_sel_hi:[0,1]
	v_pk_fma_f32 v[2:3], v[2:3], v[236:237], v[250:251] op_sel:[0,0,0] op_sel_hi:[1,0,1] neg_hi:[0,0,1]
	v_pk_mul_f32 v[250:251], v[6:7], v[240:241] op_sel:[1,1] op_sel_hi:[0,1]
	v_pk_fma_f32 v[6:7], v[6:7], v[240:241], v[250:251] op_sel:[0,0,0] op_sel_hi:[1,0,1] neg_hi:[0,0,1]
	v_pk_add_f32 v[242:243], v[0:1], v[4:5]
	v_pk_add_f32 v[244:245], v[0:1], v[4:5] neg_lo:[0,1] neg_hi:[0,1]
	v_pk_add_f32 v[246:247], v[2:3], v[6:7]
	v_pk_add_f32 v[248:249], v[2:3], v[6:7] neg_lo:[0,1] neg_hi:[0,1]
	v_pk_add_f32 v[0:1], v[242:243], v[246:247]
	v_pk_add_f32 v[2:3], v[244:245], v[248:249] op_sel:[0,1] op_sel_hi:[1,0] neg_lo:[0,1]
	v_pk_add_f32 v[4:5], v[242:243], v[246:247] neg_lo:[0,1] neg_hi:[0,1]
	v_pk_add_f32 v[6:7], v[244:245], v[248:249] op_sel:[0,1] op_sel_hi:[1,0] neg_hi:[0,1]
	s_waitcnt lgkmcnt(8)
; HD float2 cmul(float2 a, float2 b){ return make_float2(a.x*b.x - a.y*b.y, a.x*b.y + a.y*b.x); }
; HD float2 cmulc(float2 a, float2 b){ return make_float2(a.x*b.x + a.y*b.y, a.y*b.x - a.x*b.y); }
; template<bool INV, bool NOTW>
; HD void bf4c(float2* Z, int i0, int i1, int i2, int i3, float2 w1, float2 w2, float2 w3){
;   float2 a0=Z[i0], a1=Z[i1], a2=Z[i2], a3=Z[i3];
;   if (INV && !NOTW){ a1=cmulc(a1,w1); a2=cmulc(a2,w2); a3=cmulc(a3,w3); }
;   float2 s02=make_float2(a0.x+a2.x,a0.y+a2.y), d02=make_float2(a0.x-a2.x,a0.y-a2.y);
;   float2 s13=make_float2(a1.x+a3.x,a1.y+a3.y), d13=make_float2(a1.x-a3.x,a1.y-a3.y);
;   float2 y0=make_float2(s02.x+s13.x,s02.y+s13.y), y2=make_float2(s02.x-s13.x,s02.y-s13.y);
;   float2 ym=make_float2(d02.x+d13.y,d02.y-d13.x);
;   float2 yp=make_float2(d02.x-d13.y,d02.y+d13.x);
;   float2 y1, y3;
;   if (INV){ y1=yp; y3=ym; } else if (NOTW){ y1=ym; y3=yp; } else { y1=cmul(ym,w1); y2=cmul(y2,w2); y3=cmul(yp,w3); }
;   Z[i0]=y0; Z[i1]=y1; Z[i2]=y2; Z[i3]=y3;
; }
; HD int rev4_14(int p){ unsigned r = __brev((unsigned)p) >> 18; return (int)(((r & 0x2AAAu) >> 1) | ((r & 0x1555u) << 1)); }
; template<bool INV, int LQ, bool BARRIER=true>
; HD void fft_pass(float2* Z, const float2* twA, const float2* twB, int tid){
;   constexpr int q=1<<LQ; constexpr int tws=4096>>LQ;
;   if (LQ==12){
;     _Pragma("unroll 2") for (int i=0;i<8;++i){ int t=tid+512*i; int k=t;
;       float2 w1=cmul(twA[k>>6],twB[k&63]), w2=cmul(w1,w1), w3=cmul(w2,w1);
;       bf4c<INV,false>(Z,t,t+q,t+2*q,t+3*q,w1,w2,w3); }
;   } else if (LQ==10){
;     _Pragma("unroll") for (int e=0;e<2;++e){ int j=tid+512*e; int k=j*tws;
;       float2 w1=cmul(twA[k>>6],twB[k&63]), w2=cmul(w1,w1), w3=cmul(w2,w1);
;       _Pragma("unroll") for (int ip=0;ip<4;++ip){ int base=ip*4096+j; bf4c<INV,false>(Z,base,base+q,base+2*q,base+3*q,w1,w2,w3); } }
;   } else {
;     int j=tid&(q-1); int base0=((tid>>LQ)<<(LQ+2))+j;
;     float2 w1=make_float2(1.f,0.f), w2=w1, w3=w1;
;     if (LQ>0){ int k=j*tws; w1=cmul(twA[k>>6],twB[k&63]); w2=cmul(w1,w1); w3=cmul(w2,w1); }
;     _Pragma("unroll") for (int i=0;i<8;++i){ int base=base0+i*2048; bf4c<INV,(LQ==0)>(Z,base,base+q,base+2*q,base+3*q,w1,w2,w3); }
;   }
;   if (BARRIER) __syncthreads(); else asm volatile("s_waitcnt lgkmcnt(0)" ::: "memory");
; }
	v_pk_mul_f32 v[250:251], v[12:13], v[238:239] op_sel:[1,1] op_sel_hi:[0,1]
	v_pk_fma_f32 v[12:13], v[12:13], v[238:239], v[250:251] op_sel:[0,0,0] op_sel_hi:[1,0,1] neg_hi:[0,0,1]
	v_pk_mul_f32 v[250:251], v[10:11], v[236:237] op_sel:[1,1] op_sel_hi:[0,1]
	v_pk_fma_f32 v[10:11], v[10:11], v[236:237], v[250:251] op_sel:[0,0,0] op_sel_hi:[1,0,1] neg_hi:[0,0,1]
	v_pk_mul_f32 v[250:251], v[14:15], v[240:241] op_sel:[1,1] op_sel_hi:[0,1]
	v_pk_fma_f32 v[14:15], v[14:15], v[240:241], v[250:251] op_sel:[0,0,0] op_sel_hi:[1,0,1] neg_hi:[0,0,1]
	v_pk_add_f32 v[242:243], v[8:9], v[12:13]
	v_pk_add_f32 v[244:245], v[8:9], v[12:13] neg_lo:[0,1] neg_hi:[0,1]
	v_pk_add_f32 v[246:247], v[10:11], v[14:15]
	v_pk_add_f32 v[248:249], v[10:11], v[14:15] neg_lo:[0,1] neg_hi:[0,1]
	v_pk_add_f32 v[8:9], v[242:243], v[246:247]
	v_pk_add_f32 v[10:11], v[244:245], v[248:249] op_sel:[0,1] op_sel_hi:[1,0] neg_lo:[0,1]
	v_pk_add_f32 v[12:13], v[242:243], v[246:247] neg_lo:[0,1] neg_hi:[0,1]
	v_pk_add_f32 v[14:15], v[244:245], v[248:249] op_sel:[0,1] op_sel_hi:[1,0] neg_hi:[0,1]
	s_waitcnt lgkmcnt(4)
	v_pk_mul_f32 v[250:251], v[20:21], v[238:239] op_sel:[1,1] op_sel_hi:[0,1]
	v_pk_fma_f32 v[20:21], v[20:21], v[238:239], v[250:251] op_sel:[0,0,0] op_sel_hi:[1,0,1] neg_hi:[0,0,1]
	v_pk_mul_f32 v[250:251], v[18:19], v[236:237] op_sel:[1,1] op_sel_hi:[0,1]
	v_pk_fma_f32 v[18:19], v[18:19], v[236:237], v[250:251] op_sel:[0,0,0] op_sel_hi:[1,0,1] neg_hi:[0,0,1]
	v_pk_mul_f32 v[250:251], v[22:23], v[240:241] op_sel:[1,1] op_sel_hi:[0,1]
	v_pk_fma_f32 v[22:23], v[22:23], v[240:241], v[250:251] op_sel:[0,0,0] op_sel_hi:[1,0,1] neg_hi:[0,0,1]
	v_pk_add_f32 v[242:243], v[16:17], v[20:21]
	v_pk_add_f32 v[244:245], v[16:17], v[20:21] neg_lo:[0,1] neg_hi:[0,1]
	v_pk_add_f32 v[246:247], v[18:19], v[22:23]
	v_pk_add_f32 v[248:249], v[18:19], v[22:23] neg_lo:[0,1] neg_hi:[0,1]
	v_pk_add_f32 v[16:17], v[242:243], v[246:247]
	v_pk_add_f32 v[18:19], v[244:245], v[248:249] op_sel:[0,1] op_sel_hi:[1,0] neg_lo:[0,1]
	v_pk_add_f32 v[20:21], v[242:243], v[246:247] neg_lo:[0,1] neg_hi:[0,1]
	v_pk_add_f32 v[22:23], v[244:245], v[248:249] op_sel:[0,1] op_sel_hi:[1,0] neg_hi:[0,1]
	s_waitcnt lgkmcnt(0)
	v_pk_mul_f32 v[250:251], v[28:29], v[238:239] op_sel:[1,1] op_sel_hi:[0,1]
	v_pk_fma_f32 v[28:29], v[28:29], v[238:239], v[250:251] op_sel:[0,0,0] op_sel_hi:[1,0,1] neg_hi:[0,0,1]
	v_pk_mul_f32 v[250:251], v[26:27], v[236:237] op_sel:[1,1] op_sel_hi:[0,1]
	v_pk_fma_f32 v[26:27], v[26:27], v[236:237], v[250:251] op_sel:[0,0,0] op_sel_hi:[1,0,1] neg_hi:[0,0,1]
	v_pk_mul_f32 v[250:251], v[30:31], v[240:241] op_sel:[1,1] op_sel_hi:[0,1]
	v_pk_fma_f32 v[30:31], v[30:31], v[240:241], v[250:251] op_sel:[0,0,0] op_sel_hi:[1,0,1] neg_hi:[0,0,1]
	v_pk_add_f32 v[242:243], v[24:25], v[28:29]
	v_pk_add_f32 v[244:245], v[24:25], v[28:29] neg_lo:[0,1] neg_hi:[0,1]
	v_pk_add_f32 v[246:247], v[26:27], v[30:31]
	v_pk_add_f32 v[248:249], v[26:27], v[30:31] neg_lo:[0,1] neg_hi:[0,1]
	v_pk_add_f32 v[24:25], v[242:243], v[246:247]
	v_pk_add_f32 v[26:27], v[244:245], v[248:249] op_sel:[0,1] op_sel_hi:[1,0] neg_lo:[0,1]
	v_pk_add_f32 v[28:29], v[242:243], v[246:247] neg_lo:[0,1] neg_hi:[0,1]
	v_pk_add_f32 v[30:31], v[244:245], v[248:249] op_sel:[0,1] op_sel_hi:[1,0] neg_hi:[0,1]
	v_pk_mul_f32 v[250:251], v[16:17], v[82:83] op_sel:[1,1] op_sel_hi:[0,1]
	v_pk_fma_f32 v[16:17], v[16:17], v[82:83], v[250:251] op_sel:[0,0,0] op_sel_hi:[1,0,1] neg_hi:[0,0,1]
	v_pk_mul_f32 v[250:251], v[8:9], v[80:81] op_sel:[1,1] op_sel_hi:[0,1]
	v_pk_fma_f32 v[8:9], v[8:9], v[80:81], v[250:251] op_sel:[0,0,0] op_sel_hi:[1,0,1] neg_hi:[0,0,1]
	v_pk_mul_f32 v[250:251], v[24:25], v[84:85] op_sel:[1,1] op_sel_hi:[0,1]
	v_pk_fma_f32 v[24:25], v[24:25], v[84:85], v[250:251] op_sel:[0,0,0] op_sel_hi:[1,0,1] neg_hi:[0,0,1]
	v_pk_add_f32 v[242:243], v[0:1], v[16:17]
	v_pk_add_f32 v[244:245], v[0:1], v[16:17] neg_lo:[0,1] neg_hi:[0,1]
	v_pk_add_f32 v[246:247], v[8:9], v[24:25]
	v_pk_add_f32 v[248:249], v[8:9], v[24:25] neg_lo:[0,1] neg_hi:[0,1]
	v_pk_add_f32 v[0:1], v[242:243], v[246:247]
	ds_write_b64 v226, v[0:1] offset:0
	v_pk_add_f32 v[8:9], v[244:245], v[248:249] op_sel:[0,1] op_sel_hi:[1,0] neg_lo:[0,1]
	ds_write_b64 v226, v[8:9] offset:8192
	v_pk_add_f32 v[16:17], v[242:243], v[246:247] neg_lo:[0,1] neg_hi:[0,1]
	ds_write_b64 v226, v[16:17] offset:16384
	v_pk_add_f32 v[24:25], v[244:245], v[248:249] op_sel:[0,1] op_sel_hi:[1,0] neg_hi:[0,1]
	ds_write_b64 v226, v[24:25] offset:24576
	v_pk_mul_f32 v[250:251], v[18:19], v[224:225] op_sel:[1,1] op_sel_hi:[1,0] neg_lo:[0,0] neg_hi:[0,0]
	v_pk_fma_f32 v[18:19], v[18:19], v[224:225], v[250:251] op_sel:[0,0,0] op_sel_hi:[0,1,1] neg_lo:[0,0,1] neg_hi:[0,0,0]
	v_pk_mul_f32 v[250:251], v[18:19], v[82:83] op_sel:[1,1] op_sel_hi:[0,1]
	v_pk_fma_f32 v[18:19], v[18:19], v[82:83], v[250:251] op_sel:[0,0,0] op_sel_hi:[1,0,1] neg_hi:[0,0,1]
	v_pk_mul_f32 v[250:251], v[10:11], v[222:223] op_sel:[1,1] op_sel_hi:[1,0] neg_lo:[0,0] neg_hi:[0,0]
	v_pk_fma_f32 v[10:11], v[10:11], v[222:223], v[250:251] op_sel:[0,0,0] op_sel_hi:[0,1,1] neg_lo:[0,0,1] neg_hi:[0,0,0]
	v_pk_mul_f32 v[250:251], v[10:11], v[80:81] op_sel:[1,1] op_sel_hi:[0,1]
	v_pk_fma_f32 v[10:11], v[10:11], v[80:81], v[250:251] op_sel:[0,0,0] op_sel_hi:[1,0,1] neg_hi:[0,0,1]
	v_pk_mul_f32 v[250:251], v[26:27], v[222:223] op_sel:[1,0] op_sel_hi:[1,1] neg_lo:[0,0] neg_hi:[0,0]
	v_pk_fma_f32 v[26:27], v[26:27], v[222:223], v[250:251] op_sel:[0,1,0] op_sel_hi:[0,0,1] neg_lo:[0,0,1] neg_hi:[0,0,0]
	v_pk_mul_f32 v[250:251], v[26:27], v[84:85] op_sel:[1,1] op_sel_hi:[0,1]
	v_pk_fma_f32 v[26:27], v[26:27], v[84:85], v[250:251] op_sel:[0,0,0] op_sel_hi:[1,0,1] neg_hi:[0,0,1]
; HD float2 cmul(float2 a, float2 b){ return make_float2(a.x*b.x - a.y*b.y, a.x*b.y + a.y*b.x); }
; HD float2 cmulc(float2 a, float2 b){ return make_float2(a.x*b.x + a.y*b.y, a.y*b.x - a.x*b.y); }
; template<bool INV, bool NOTW>
; HD void bf4c(float2* Z, int i0, int i1, int i2, int i3, float2 w1, float2 w2, float2 w3){
;   float2 a0=Z[i0], a1=Z[i1], a2=Z[i2], a3=Z[i3];
;   if (INV && !NOTW){ a1=cmulc(a1,w1); a2=cmulc(a2,w2); a3=cmulc(a3,w3); }
;   float2 s02=make_float2(a0.x+a2.x,a0.y+a2.y), d02=make_float2(a0.x-a2.x,a0.y-a2.y);
;   float2 s13=make_float2(a1.x+a3.x,a1.y+a3.y), d13=make_float2(a1.x-a3.x,a1.y-a3.y);
;   float2 y0=make_float2(s02.x+s13.x,s02.y+s13.y), y2=make_float2(s02.x-s13.x,s02.y-s13.y);
;   float2 ym=make_float2(d02.x+d13.y,d02.y-d13.x);
;   float2 yp=make_float2(d02.x-d13.y,d02.y+d13.x);
;   float2 y1, y3;
;   if (INV){ y1=yp; y3=ym; } else if (NOTW){ y1=ym; y3=yp; } else { y1=cmul(ym,w1); y2=cmul(y2,w2); y3=cmul(yp,w3); }
;   Z[i0]=y0; Z[i1]=y1; Z[i2]=y2; Z[i3]=y3;
; }
; HD int rev4_14(int p){ unsigned r = __brev((unsigned)p) >> 18; return (int)(((r & 0x2AAAu) >> 1) | ((r & 0x1555u) << 1)); }
; template<bool INV, int LQ, bool BARRIER=true>
; HD void fft_pass(float2* Z, const float2* twA, const float2* twB, int tid){
;   constexpr int q=1<<LQ; constexpr int tws=4096>>LQ;
;   if (LQ==12){
;     _Pragma("unroll 2") for (int i=0;i<8;++i){ int t=tid+512*i; int k=t;
;       float2 w1=cmul(twA[k>>6],twB[k&63]), w2=cmul(w1,w1), w3=cmul(w2,w1);
;       bf4c<INV,false>(Z,t,t+q,t+2*q,t+3*q,w1,w2,w3); }
;   } else if (LQ==10){
;     _Pragma("unroll") for (int e=0;e<2;++e){ int j=tid+512*e; int k=j*tws;
;       float2 w1=cmul(twA[k>>6],twB[k&63]), w2=cmul(w1,w1), w3=cmul(w2,w1);
;       _Pragma("unroll") for (int ip=0;ip<4;++ip){ int base=ip*4096+j; bf4c<INV,false>(Z,base,base+q,base+2*q,base+3*q,w1,w2,w3); } }
;   } else {
;     int j=tid&(q-1); int base0=((tid>>LQ)<<(LQ+2))+j;
;     float2 w1=make_float2(1.f,0.f), w2=w1, w3=w1;
;     if (LQ>0){ int k=j*tws; w1=cmul(twA[k>>6],twB[k&63]); w2=cmul(w1,w1); w3=cmul(w2,w1); }
;     _Pragma("unroll") for (int i=0;i<8;++i){ int base=base0+i*2048; bf4c<INV,(LQ==0)>(Z,base,base+q,base+2*q,base+3*q,w1,w2,w3); }
;   }
;   if (BARRIER) __syncthreads(); else asm volatile("s_waitcnt lgkmcnt(0)" ::: "memory");
; }
	v_pk_add_f32 v[242:243], v[2:3], v[18:19]
	v_pk_add_f32 v[244:245], v[2:3], v[18:19] neg_lo:[0,1] neg_hi:[0,1]
	v_pk_add_f32 v[246:247], v[10:11], v[26:27]
	v_pk_add_f32 v[248:249], v[10:11], v[26:27] neg_lo:[0,1] neg_hi:[0,1]
	v_pk_add_f32 v[2:3], v[242:243], v[246:247]
	ds_write_b64 v226, v[2:3] offset:2048
	v_pk_add_f32 v[10:11], v[244:245], v[248:249] op_sel:[0,1] op_sel_hi:[1,0] neg_lo:[0,1]
	ds_write_b64 v226, v[10:11] offset:10240
	v_pk_add_f32 v[18:19], v[242:243], v[246:247] neg_lo:[0,1] neg_hi:[0,1]
	ds_write_b64 v226, v[18:19] offset:18432
	v_pk_add_f32 v[26:27], v[244:245], v[248:249] op_sel:[0,1] op_sel_hi:[1,0] neg_hi:[0,1]
	ds_write_b64 v226, v[26:27] offset:26624
	v_pk_add_f32 v[20:21], v[20:21], 0 op_sel:[1,0] op_sel_hi:[0,0] neg_lo:[1,0]
	v_pk_mul_f32 v[250:251], v[20:21], v[82:83] op_sel:[1,1] op_sel_hi:[0,1]
	v_pk_fma_f32 v[20:21], v[20:21], v[82:83], v[250:251] op_sel:[0,0,0] op_sel_hi:[1,0,1] neg_hi:[0,0,1]
	v_pk_mul_f32 v[250:251], v[12:13], v[224:225] op_sel:[1,1] op_sel_hi:[1,0] neg_lo:[0,0] neg_hi:[0,0]
	v_pk_fma_f32 v[12:13], v[12:13], v[224:225], v[250:251] op_sel:[0,0,0] op_sel_hi:[0,1,1] neg_lo:[0,0,1] neg_hi:[0,0,0]
	v_pk_mul_f32 v[250:251], v[12:13], v[80:81] op_sel:[1,1] op_sel_hi:[0,1]
	v_pk_fma_f32 v[12:13], v[12:13], v[80:81], v[250:251] op_sel:[0,0,0] op_sel_hi:[1,0,1] neg_hi:[0,0,1]
	v_pk_mul_f32 v[250:251], v[28:29], v[224:225] op_sel:[1,1] op_sel_hi:[1,0] neg_lo:[0,0] neg_hi:[0,1]
	v_pk_fma_f32 v[28:29], v[28:29], v[224:225], v[250:251] op_sel:[0,0,0] op_sel_hi:[0,1,1] neg_lo:[0,1,1] neg_hi:[0,0,0]
	v_pk_mul_f32 v[250:251], v[28:29], v[84:85] op_sel:[1,1] op_sel_hi:[0,1]
	v_pk_fma_f32 v[28:29], v[28:29], v[84:85], v[250:251] op_sel:[0,0,0] op_sel_hi:[1,0,1] neg_hi:[0,0,1]
	v_pk_add_f32 v[242:243], v[4:5], v[20:21]
	v_pk_add_f32 v[244:245], v[4:5], v[20:21] neg_lo:[0,1] neg_hi:[0,1]
	v_pk_add_f32 v[246:247], v[12:13], v[28:29]
	v_pk_add_f32 v[248:249], v[12:13], v[28:29] neg_lo:[0,1] neg_hi:[0,1]
	v_pk_add_f32 v[4:5], v[242:243], v[246:247]
	ds_write_b64 v226, v[4:5] offset:4096
	v_pk_add_f32 v[12:13], v[244:245], v[248:249] op_sel:[0,1] op_sel_hi:[1,0] neg_lo:[0,1]
	ds_write_b64 v226, v[12:13] offset:12288
	v_pk_add_f32 v[20:21], v[242:243], v[246:247] neg_lo:[0,1] neg_hi:[0,1]
	ds_write_b64 v226, v[20:21] offset:20480
	v_pk_add_f32 v[28:29], v[244:245], v[248:249] op_sel:[0,1] op_sel_hi:[1,0] neg_hi:[0,1]
	ds_write_b64 v226, v[28:29] offset:28672
	v_pk_mul_f32 v[250:251], v[22:23], v[224:225] op_sel:[1,1] op_sel_hi:[1,0] neg_lo:[0,0] neg_hi:[0,1]
	v_pk_fma_f32 v[22:23], v[22:23], v[224:225], v[250:251] op_sel:[0,0,0] op_sel_hi:[0,1,1] neg_lo:[0,1,1] neg_hi:[0,0,0]
	v_pk_mul_f32 v[250:251], v[22:23], v[82:83] op_sel:[1,1] op_sel_hi:[0,1]
	v_pk_fma_f32 v[22:23], v[22:23], v[82:83], v[250:251] op_sel:[0,0,0] op_sel_hi:[1,0,1] neg_hi:[0,0,1]
	v_pk_mul_f32 v[250:251], v[14:15], v[222:223] op_sel:[1,0] op_sel_hi:[1,1] neg_lo:[0,0] neg_hi:[0,0]
	v_pk_fma_f32 v[14:15], v[14:15], v[222:223], v[250:251] op_sel:[0,1,0] op_sel_hi:[0,0,1] neg_lo:[0,0,1] neg_hi:[0,0,0]
	v_pk_mul_f32 v[250:251], v[14:15], v[80:81] op_sel:[1,1] op_sel_hi:[0,1]
	v_pk_fma_f32 v[14:15], v[14:15], v[80:81], v[250:251] op_sel:[0,0,0] op_sel_hi:[1,0,1] neg_hi:[0,0,1]
	v_pk_mul_f32 v[250:251], v[30:31], v[222:223] op_sel:[1,1] op_sel_hi:[1,0] neg_lo:[0,1] neg_hi:[0,1]
	v_pk_fma_f32 v[30:31], v[30:31], v[222:223], v[250:251] op_sel:[0,0,0] op_sel_hi:[0,1,1] neg_lo:[0,1,1] neg_hi:[0,1,0]
	v_pk_mul_f32 v[250:251], v[30:31], v[84:85] op_sel:[1,1] op_sel_hi:[0,1]
	v_pk_fma_f32 v[30:31], v[30:31], v[84:85], v[250:251] op_sel:[0,0,0] op_sel_hi:[1,0,1] neg_hi:[0,0,1]
	v_pk_add_f32 v[242:243], v[6:7], v[22:23]
	v_pk_add_f32 v[244:245], v[6:7], v[22:23] neg_lo:[0,1] neg_hi:[0,1]
	v_pk_add_f32 v[246:247], v[14:15], v[30:31]
	v_pk_add_f32 v[248:249], v[14:15], v[30:31] neg_lo:[0,1] neg_hi:[0,1]
	v_pk_add_f32 v[6:7], v[242:243], v[246:247]
	ds_write_b64 v226, v[6:7] offset:6144
	v_pk_add_f32 v[14:15], v[244:245], v[248:249] op_sel:[0,1] op_sel_hi:[1,0] neg_lo:[0,1]
	ds_write_b64 v226, v[14:15] offset:14336
	v_pk_add_f32 v[22:23], v[242:243], v[246:247] neg_lo:[0,1] neg_hi:[0,1]
	ds_write_b64 v226, v[22:23] offset:22528
	v_pk_add_f32 v[30:31], v[244:245], v[248:249] op_sel:[0,1] op_sel_hi:[1,0] neg_hi:[0,1]
	ds_write_b64 v226, v[30:31] offset:30720
	ds_read_b64 v[0:1], v227 offset:0
	ds_read_b64 v[2:3], v227 offset:2048
	ds_read_b64 v[4:5], v227 offset:4096
	ds_read_b64 v[6:7], v227 offset:6144
	ds_read_b64 v[8:9], v227 offset:8192
	ds_read_b64 v[10:11], v227 offset:10240
	ds_read_b64 v[12:13], v227 offset:12288
	ds_read_b64 v[14:15], v227 offset:14336
	ds_read_b64 v[16:17], v227 offset:16384
	ds_read_b64 v[18:19], v227 offset:18432
	ds_read_b64 v[20:21], v227 offset:20480
	ds_read_b64 v[22:23], v227 offset:22528
	ds_read_b64 v[24:25], v227 offset:24576
	ds_read_b64 v[26:27], v227 offset:26624
	ds_read_b64 v[28:29], v227 offset:28672
	ds_read_b64 v[30:31], v227 offset:30720
	s_waitcnt lgkmcnt(12)
	v_pk_mul_f32 v[250:251], v[4:5], v[238:239] op_sel:[1,1] op_sel_hi:[0,1]
	v_pk_fma_f32 v[4:5], v[4:5], v[238:239], v[250:251] op_sel:[0,0,0] op_sel_hi:[1,0,1] neg_hi:[0,0,1]
	v_pk_mul_f32 v[250:251], v[2:3], v[236:237] op_sel:[1,1] op_sel_hi:[0,1]
	v_pk_fma_f32 v[2:3], v[2:3], v[236:237], v[250:251] op_sel:[0,0,0] op_sel_hi:[1,0,1] neg_hi:[0,0,1]
	v_pk_mul_f32 v[250:251], v[6:7], v[240:241] op_sel:[1,1] op_sel_hi:[0,1]
	v_pk_fma_f32 v[6:7], v[6:7], v[240:241], v[250:251] op_sel:[0,0,0] op_sel_hi:[1,0,1] neg_hi:[0,0,1]
	v_pk_add_f32 v[242:243], v[0:1], v[4:5]
	v_pk_add_f32 v[244:245], v[0:1], v[4:5] neg_lo:[0,1] neg_hi:[0,1]
	v_pk_add_f32 v[246:247], v[2:3], v[6:7]
	v_pk_add_f32 v[248:249], v[2:3], v[6:7] neg_lo:[0,1] neg_hi:[0,1]
	v_pk_add_f32 v[0:1], v[242:243], v[246:247]
	v_pk_add_f32 v[2:3], v[244:245], v[248:249] op_sel:[0,1] op_sel_hi:[1,0] neg_lo:[0,1]
	v_pk_add_f32 v[4:5], v[242:243], v[246:247] neg_lo:[0,1] neg_hi:[0,1]
	v_pk_add_f32 v[6:7], v[244:245], v[248:249] op_sel:[0,1] op_sel_hi:[1,0] neg_hi:[0,1]
	s_waitcnt lgkmcnt(8)
; HD float2 cmul(float2 a, float2 b){ return make_float2(a.x*b.x - a.y*b.y, a.x*b.y + a.y*b.x); }
; HD float2 cmulc(float2 a, float2 b){ return make_float2(a.x*b.x + a.y*b.y, a.y*b.x - a.x*b.y); }
; template<bool INV, bool NOTW>
; HD void bf4c(float2* Z, int i0, int i1, int i2, int i3, float2 w1, float2 w2, float2 w3){
;   float2 a0=Z[i0], a1=Z[i1], a2=Z[i2], a3=Z[i3];
;   if (INV && !NOTW){ a1=cmulc(a1,w1); a2=cmulc(a2,w2); a3=cmulc(a3,w3); }
;   float2 s02=make_float2(a0.x+a2.x,a0.y+a2.y), d02=make_float2(a0.x-a2.x,a0.y-a2.y);
;   float2 s13=make_float2(a1.x+a3.x,a1.y+a3.y), d13=make_float2(a1.x-a3.x,a1.y-a3.y);
;   float2 y0=make_float2(s02.x+s13.x,s02.y+s13.y), y2=make_float2(s02.x-s13.x,s02.y-s13.y);
;   float2 ym=make_float2(d02.x+d13.y,d02.y-d13.x);
;   float2 yp=make_float2(d02.x-d13.y,d02.y+d13.x);
;   float2 y1, y3;
;   if (INV){ y1=yp; y3=ym; } else if (NOTW){ y1=ym; y3=yp; } else { y1=cmul(ym,w1); y2=cmul(y2,w2); y3=cmul(yp,w3); }
;   Z[i0]=y0; Z[i1]=y1; Z[i2]=y2; Z[i3]=y3;
; }
; HD int rev4_14(int p){ unsigned r = __brev((unsigned)p) >> 18; return (int)(((r & 0x2AAAu) >> 1) | ((r & 0x1555u) << 1)); }
; template<bool INV, int LQ, bool BARRIER=true>
; HD void fft_pass(float2* Z, const float2* twA, const float2* twB, int tid){
;   constexpr int q=1<<LQ; constexpr int tws=4096>>LQ;
;   if (LQ==12){
;     _Pragma("unroll 2") for (int i=0;i<8;++i){ int t=tid+512*i; int k=t;
;       float2 w1=cmul(twA[k>>6],twB[k&63]), w2=cmul(w1,w1), w3=cmul(w2,w1);
;       bf4c<INV,false>(Z,t,t+q,t+2*q,t+3*q,w1,w2,w3); }
;   } else if (LQ==10){
;     _Pragma("unroll") for (int e=0;e<2;++e){ int j=tid+512*e; int k=j*tws;
;       float2 w1=cmul(twA[k>>6],twB[k&63]), w2=cmul(w1,w1), w3=cmul(w2,w1);
;       _Pragma("unroll") for (int ip=0;ip<4;++ip){ int base=ip*4096+j; bf4c<INV,false>(Z,base,base+q,base+2*q,base+3*q,w1,w2,w3); } }
;   } else {
;     int j=tid&(q-1); int base0=((tid>>LQ)<<(LQ+2))+j;
;     float2 w1=make_float2(1.f,0.f), w2=w1, w3=w1;
;     if (LQ>0){ int k=j*tws; w1=cmul(twA[k>>6],twB[k&63]); w2=cmul(w1,w1); w3=cmul(w2,w1); }
;     _Pragma("unroll") for (int i=0;i<8;++i){ int base=base0+i*2048; bf4c<INV,(LQ==0)>(Z,base,base+q,base+2*q,base+3*q,w1,w2,w3); }
;   }
;   if (BARRIER) __syncthreads(); else asm volatile("s_waitcnt lgkmcnt(0)" ::: "memory");
; }
	v_pk_mul_f32 v[250:251], v[12:13], v[238:239] op_sel:[1,1] op_sel_hi:[0,1]
	v_pk_fma_f32 v[12:13], v[12:13], v[238:239], v[250:251] op_sel:[0,0,0] op_sel_hi:[1,0,1] neg_hi:[0,0,1]
	v_pk_mul_f32 v[250:251], v[10:11], v[236:237] op_sel:[1,1] op_sel_hi:[0,1]
	v_pk_fma_f32 v[10:11], v[10:11], v[236:237], v[250:251] op_sel:[0,0,0] op_sel_hi:[1,0,1] neg_hi:[0,0,1]
	v_pk_mul_f32 v[250:251], v[14:15], v[240:241] op_sel:[1,1] op_sel_hi:[0,1]
	v_pk_fma_f32 v[14:15], v[14:15], v[240:241], v[250:251] op_sel:[0,0,0] op_sel_hi:[1,0,1] neg_hi:[0,0,1]
	v_pk_add_f32 v[242:243], v[8:9], v[12:13]
	v_pk_add_f32 v[244:245], v[8:9], v[12:13] neg_lo:[0,1] neg_hi:[0,1]
	v_pk_add_f32 v[246:247], v[10:11], v[14:15]
	v_pk_add_f32 v[248:249], v[10:11], v[14:15] neg_lo:[0,1] neg_hi:[0,1]
	v_pk_add_f32 v[8:9], v[242:243], v[246:247]
	v_pk_add_f32 v[10:11], v[244:245], v[248:249] op_sel:[0,1] op_sel_hi:[1,0] neg_lo:[0,1]
	v_pk_add_f32 v[12:13], v[242:243], v[246:247] neg_lo:[0,1] neg_hi:[0,1]
	v_pk_add_f32 v[14:15], v[244:245], v[248:249] op_sel:[0,1] op_sel_hi:[1,0] neg_hi:[0,1]
	s_waitcnt lgkmcnt(4)
	v_pk_mul_f32 v[250:251], v[20:21], v[238:239] op_sel:[1,1] op_sel_hi:[0,1]
	v_pk_fma_f32 v[20:21], v[20:21], v[238:239], v[250:251] op_sel:[0,0,0] op_sel_hi:[1,0,1] neg_hi:[0,0,1]
	v_pk_mul_f32 v[250:251], v[18:19], v[236:237] op_sel:[1,1] op_sel_hi:[0,1]
	v_pk_fma_f32 v[18:19], v[18:19], v[236:237], v[250:251] op_sel:[0,0,0] op_sel_hi:[1,0,1] neg_hi:[0,0,1]
	v_pk_mul_f32 v[250:251], v[22:23], v[240:241] op_sel:[1,1] op_sel_hi:[0,1]
	v_pk_fma_f32 v[22:23], v[22:23], v[240:241], v[250:251] op_sel:[0,0,0] op_sel_hi:[1,0,1] neg_hi:[0,0,1]
	v_pk_add_f32 v[242:243], v[16:17], v[20:21]
	v_pk_add_f32 v[244:245], v[16:17], v[20:21] neg_lo:[0,1] neg_hi:[0,1]
	v_pk_add_f32 v[246:247], v[18:19], v[22:23]
	v_pk_add_f32 v[248:249], v[18:19], v[22:23] neg_lo:[0,1] neg_hi:[0,1]
	v_pk_add_f32 v[16:17], v[242:243], v[246:247]
	v_pk_add_f32 v[18:19], v[244:245], v[248:249] op_sel:[0,1] op_sel_hi:[1,0] neg_lo:[0,1]
	v_pk_add_f32 v[20:21], v[242:243], v[246:247] neg_lo:[0,1] neg_hi:[0,1]
	v_pk_add_f32 v[22:23], v[244:245], v[248:249] op_sel:[0,1] op_sel_hi:[1,0] neg_hi:[0,1]
	s_waitcnt lgkmcnt(0)
	v_pk_mul_f32 v[250:251], v[28:29], v[238:239] op_sel:[1,1] op_sel_hi:[0,1]
	v_pk_fma_f32 v[28:29], v[28:29], v[238:239], v[250:251] op_sel:[0,0,0] op_sel_hi:[1,0,1] neg_hi:[0,0,1]
	v_pk_mul_f32 v[250:251], v[26:27], v[236:237] op_sel:[1,1] op_sel_hi:[0,1]
	v_pk_fma_f32 v[26:27], v[26:27], v[236:237], v[250:251] op_sel:[0,0,0] op_sel_hi:[1,0,1] neg_hi:[0,0,1]
	v_pk_mul_f32 v[250:251], v[30:31], v[240:241] op_sel:[1,1] op_sel_hi:[0,1]
	v_pk_fma_f32 v[30:31], v[30:31], v[240:241], v[250:251] op_sel:[0,0,0] op_sel_hi:[1,0,1] neg_hi:[0,0,1]
	v_pk_add_f32 v[242:243], v[24:25], v[28:29]
	v_pk_add_f32 v[244:245], v[24:25], v[28:29] neg_lo:[0,1] neg_hi:[0,1]
	v_pk_add_f32 v[246:247], v[26:27], v[30:31]
	v_pk_add_f32 v[248:249], v[26:27], v[30:31] neg_lo:[0,1] neg_hi:[0,1]
	v_pk_add_f32 v[24:25], v[242:243], v[246:247]
	v_pk_add_f32 v[26:27], v[244:245], v[248:249] op_sel:[0,1] op_sel_hi:[1,0] neg_lo:[0,1]
	v_pk_add_f32 v[28:29], v[242:243], v[246:247] neg_lo:[0,1] neg_hi:[0,1]
	v_pk_add_f32 v[30:31], v[244:245], v[248:249] op_sel:[0,1] op_sel_hi:[1,0] neg_hi:[0,1]
	v_pk_mul_f32 v[250:251], v[16:17], v[82:83] op_sel:[1,1] op_sel_hi:[0,1]
	v_pk_fma_f32 v[16:17], v[16:17], v[82:83], v[250:251] op_sel:[0,0,0] op_sel_hi:[1,0,1] neg_hi:[0,0,1]
	v_pk_mul_f32 v[250:251], v[8:9], v[80:81] op_sel:[1,1] op_sel_hi:[0,1]
	v_pk_fma_f32 v[8:9], v[8:9], v[80:81], v[250:251] op_sel:[0,0,0] op_sel_hi:[1,0,1] neg_hi:[0,0,1]
	v_pk_mul_f32 v[250:251], v[24:25], v[84:85] op_sel:[1,1] op_sel_hi:[0,1]
	v_pk_fma_f32 v[24:25], v[24:25], v[84:85], v[250:251] op_sel:[0,0,0] op_sel_hi:[1,0,1] neg_hi:[0,0,1]
	v_pk_add_f32 v[242:243], v[0:1], v[16:17]
	v_pk_add_f32 v[244:245], v[0:1], v[16:17] neg_lo:[0,1] neg_hi:[0,1]
	v_pk_add_f32 v[246:247], v[8:9], v[24:25]
	v_pk_add_f32 v[248:249], v[8:9], v[24:25] neg_lo:[0,1] neg_hi:[0,1]
	v_pk_add_f32 v[0:1], v[242:243], v[246:247]
	ds_write_b64 v227, v[0:1] offset:0
	v_pk_add_f32 v[8:9], v[244:245], v[248:249] op_sel:[0,1] op_sel_hi:[1,0] neg_lo:[0,1]
	ds_write_b64 v227, v[8:9] offset:8192
	v_pk_add_f32 v[16:17], v[242:243], v[246:247] neg_lo:[0,1] neg_hi:[0,1]
	ds_write_b64 v227, v[16:17] offset:16384
	v_pk_add_f32 v[24:25], v[244:245], v[248:249] op_sel:[0,1] op_sel_hi:[1,0] neg_hi:[0,1]
	ds_write_b64 v227, v[24:25] offset:24576
	v_pk_mul_f32 v[250:251], v[18:19], v[224:225] op_sel:[1,1] op_sel_hi:[1,0] neg_lo:[0,0] neg_hi:[0,0]
	v_pk_fma_f32 v[18:19], v[18:19], v[224:225], v[250:251] op_sel:[0,0,0] op_sel_hi:[0,1,1] neg_lo:[0,0,1] neg_hi:[0,0,0]
	v_pk_mul_f32 v[250:251], v[18:19], v[82:83] op_sel:[1,1] op_sel_hi:[0,1]
	v_pk_fma_f32 v[18:19], v[18:19], v[82:83], v[250:251] op_sel:[0,0,0] op_sel_hi:[1,0,1] neg_hi:[0,0,1]
	v_pk_mul_f32 v[250:251], v[10:11], v[222:223] op_sel:[1,1] op_sel_hi:[1,0] neg_lo:[0,0] neg_hi:[0,0]
	v_pk_fma_f32 v[10:11], v[10:11], v[222:223], v[250:251] op_sel:[0,0,0] op_sel_hi:[0,1,1] neg_lo:[0,0,1] neg_hi:[0,0,0]
	v_pk_mul_f32 v[250:251], v[10:11], v[80:81] op_sel:[1,1] op_sel_hi:[0,1]
	v_pk_fma_f32 v[10:11], v[10:11], v[80:81], v[250:251] op_sel:[0,0,0] op_sel_hi:[1,0,1] neg_hi:[0,0,1]
	v_pk_mul_f32 v[250:251], v[26:27], v[222:223] op_sel:[1,0] op_sel_hi:[1,1] neg_lo:[0,0] neg_hi:[0,0]
	v_pk_fma_f32 v[26:27], v[26:27], v[222:223], v[250:251] op_sel:[0,1,0] op_sel_hi:[0,0,1] neg_lo:[0,0,1] neg_hi:[0,0,0]
	v_pk_mul_f32 v[250:251], v[26:27], v[84:85] op_sel:[1,1] op_sel_hi:[0,1]
	v_pk_fma_f32 v[26:27], v[26:27], v[84:85], v[250:251] op_sel:[0,0,0] op_sel_hi:[1,0,1] neg_hi:[0,0,1]
; HD float2 cmul(float2 a, float2 b){ return make_float2(a.x*b.x - a.y*b.y, a.x*b.y + a.y*b.x); }
; HD float2 cmulc(float2 a, float2 b){ return make_float2(a.x*b.x + a.y*b.y, a.y*b.x - a.x*b.y); }
; template<bool INV, bool NOTW>
; HD void bf4c(float2* Z, int i0, int i1, int i2, int i3, float2 w1, float2 w2, float2 w3){
;   float2 a0=Z[i0], a1=Z[i1], a2=Z[i2], a3=Z[i3];
;   if (INV && !NOTW){ a1=cmulc(a1,w1); a2=cmulc(a2,w2); a3=cmulc(a3,w3); }
;   float2 s02=make_float2(a0.x+a2.x,a0.y+a2.y), d02=make_float2(a0.x-a2.x,a0.y-a2.y);
;   float2 s13=make_float2(a1.x+a3.x,a1.y+a3.y), d13=make_float2(a1.x-a3.x,a1.y-a3.y);
;   float2 y0=make_float2(s02.x+s13.x,s02.y+s13.y), y2=make_float2(s02.x-s13.x,s02.y-s13.y);
;   float2 ym=make_float2(d02.x+d13.y,d02.y-d13.x);
;   float2 yp=make_float2(d02.x-d13.y,d02.y+d13.x);
;   float2 y1, y3;
;   if (INV){ y1=yp; y3=ym; } else if (NOTW){ y1=ym; y3=yp; } else { y1=cmul(ym,w1); y2=cmul(y2,w2); y3=cmul(yp,w3); }
;   Z[i0]=y0; Z[i1]=y1; Z[i2]=y2; Z[i3]=y3;
; }
; HD int rev4_14(int p){ unsigned r = __brev((unsigned)p) >> 18; return (int)(((r & 0x2AAAu) >> 1) | ((r & 0x1555u) << 1)); }
; template<bool INV, int LQ, bool BARRIER=true>
; HD void fft_pass(float2* Z, const float2* twA, const float2* twB, int tid){
;   constexpr int q=1<<LQ; constexpr int tws=4096>>LQ;
;   if (LQ==12){
;     _Pragma("unroll 2") for (int i=0;i<8;++i){ int t=tid+512*i; int k=t;
;       float2 w1=cmul(twA[k>>6],twB[k&63]), w2=cmul(w1,w1), w3=cmul(w2,w1);
;       bf4c<INV,false>(Z,t,t+q,t+2*q,t+3*q,w1,w2,w3); }
;   } else if (LQ==10){
;     _Pragma("unroll") for (int e=0;e<2;++e){ int j=tid+512*e; int k=j*tws;
;       float2 w1=cmul(twA[k>>6],twB[k&63]), w2=cmul(w1,w1), w3=cmul(w2,w1);
;       _Pragma("unroll") for (int ip=0;ip<4;++ip){ int base=ip*4096+j; bf4c<INV,false>(Z,base,base+q,base+2*q,base+3*q,w1,w2,w3); } }
;   } else {
;     int j=tid&(q-1); int base0=((tid>>LQ)<<(LQ+2))+j;
;     float2 w1=make_float2(1.f,0.f), w2=w1, w3=w1;
;     if (LQ>0){ int k=j*tws; w1=cmul(twA[k>>6],twB[k&63]); w2=cmul(w1,w1); w3=cmul(w2,w1); }
;     _Pragma("unroll") for (int i=0;i<8;++i){ int base=base0+i*2048; bf4c<INV,(LQ==0)>(Z,base,base+q,base+2*q,base+3*q,w1,w2,w3); }
;   }
;   if (BARRIER) __syncthreads(); else asm volatile("s_waitcnt lgkmcnt(0)" ::: "memory");
; }
	v_pk_add_f32 v[242:243], v[2:3], v[18:19]
	v_pk_add_f32 v[244:245], v[2:3], v[18:19] neg_lo:[0,1] neg_hi:[0,1]
	v_pk_add_f32 v[246:247], v[10:11], v[26:27]
	v_pk_add_f32 v[248:249], v[10:11], v[26:27] neg_lo:[0,1] neg_hi:[0,1]
	v_pk_add_f32 v[2:3], v[242:243], v[246:247]
	ds_write_b64 v227, v[2:3] offset:2048
	v_pk_add_f32 v[10:11], v[244:245], v[248:249] op_sel:[0,1] op_sel_hi:[1,0] neg_lo:[0,1]
	ds_write_b64 v227, v[10:11] offset:10240
	v_pk_add_f32 v[18:19], v[242:243], v[246:247] neg_lo:[0,1] neg_hi:[0,1]
	ds_write_b64 v227, v[18:19] offset:18432
	v_pk_add_f32 v[26:27], v[244:245], v[248:249] op_sel:[0,1] op_sel_hi:[1,0] neg_hi:[0,1]
	ds_write_b64 v227, v[26:27] offset:26624
	v_pk_add_f32 v[20:21], v[20:21], 0 op_sel:[1,0] op_sel_hi:[0,0] neg_lo:[1,0]
	v_pk_mul_f32 v[250:251], v[20:21], v[82:83] op_sel:[1,1] op_sel_hi:[0,1]
	v_pk_fma_f32 v[20:21], v[20:21], v[82:83], v[250:251] op_sel:[0,0,0] op_sel_hi:[1,0,1] neg_hi:[0,0,1]
	v_pk_mul_f32 v[250:251], v[12:13], v[224:225] op_sel:[1,1] op_sel_hi:[1,0] neg_lo:[0,0] neg_hi:[0,0]
	v_pk_fma_f32 v[12:13], v[12:13], v[224:225], v[250:251] op_sel:[0,0,0] op_sel_hi:[0,1,1] neg_lo:[0,0,1] neg_hi:[0,0,0]
	v_pk_mul_f32 v[250:251], v[12:13], v[80:81] op_sel:[1,1] op_sel_hi:[0,1]
	v_pk_fma_f32 v[12:13], v[12:13], v[80:81], v[250:251] op_sel:[0,0,0] op_sel_hi:[1,0,1] neg_hi:[0,0,1]
	v_pk_mul_f32 v[250:251], v[28:29], v[224:225] op_sel:[1,1] op_sel_hi:[1,0] neg_lo:[0,0] neg_hi:[0,1]
	v_pk_fma_f32 v[28:29], v[28:29], v[224:225], v[250:251] op_sel:[0,0,0] op_sel_hi:[0,1,1] neg_lo:[0,1,1] neg_hi:[0,0,0]
	v_pk_mul_f32 v[250:251], v[28:29], v[84:85] op_sel:[1,1] op_sel_hi:[0,1]
	v_pk_fma_f32 v[28:29], v[28:29], v[84:85], v[250:251] op_sel:[0,0,0] op_sel_hi:[1,0,1] neg_hi:[0,0,1]
	v_pk_add_f32 v[242:243], v[4:5], v[20:21]
	v_pk_add_f32 v[244:245], v[4:5], v[20:21] neg_lo:[0,1] neg_hi:[0,1]
	v_pk_add_f32 v[246:247], v[12:13], v[28:29]
	v_pk_add_f32 v[248:249], v[12:13], v[28:29] neg_lo:[0,1] neg_hi:[0,1]
	v_pk_add_f32 v[4:5], v[242:243], v[246:247]
	ds_write_b64 v227, v[4:5] offset:4096
	v_pk_add_f32 v[12:13], v[244:245], v[248:249] op_sel:[0,1] op_sel_hi:[1,0] neg_lo:[0,1]
	ds_write_b64 v227, v[12:13] offset:12288
	v_pk_add_f32 v[20:21], v[242:243], v[246:247] neg_lo:[0,1] neg_hi:[0,1]
	ds_write_b64 v227, v[20:21] offset:20480
	v_pk_add_f32 v[28:29], v[244:245], v[248:249] op_sel:[0,1] op_sel_hi:[1,0] neg_hi:[0,1]
	ds_write_b64 v227, v[28:29] offset:28672
	v_pk_mul_f32 v[250:251], v[22:23], v[224:225] op_sel:[1,1] op_sel_hi:[1,0] neg_lo:[0,0] neg_hi:[0,1]
	v_pk_fma_f32 v[22:23], v[22:23], v[224:225], v[250:251] op_sel:[0,0,0] op_sel_hi:[0,1,1] neg_lo:[0,1,1] neg_hi:[0,0,0]
	v_pk_mul_f32 v[250:251], v[22:23], v[82:83] op_sel:[1,1] op_sel_hi:[0,1]
	v_pk_fma_f32 v[22:23], v[22:23], v[82:83], v[250:251] op_sel:[0,0,0] op_sel_hi:[1,0,1] neg_hi:[0,0,1]
	v_pk_mul_f32 v[250:251], v[14:15], v[222:223] op_sel:[1,0] op_sel_hi:[1,1] neg_lo:[0,0] neg_hi:[0,0]
	v_pk_fma_f32 v[14:15], v[14:15], v[222:223], v[250:251] op_sel:[0,1,0] op_sel_hi:[0,0,1] neg_lo:[0,0,1] neg_hi:[0,0,0]
	v_pk_mul_f32 v[250:251], v[14:15], v[80:81] op_sel:[1,1] op_sel_hi:[0,1]
	v_pk_fma_f32 v[14:15], v[14:15], v[80:81], v[250:251] op_sel:[0,0,0] op_sel_hi:[1,0,1] neg_hi:[0,0,1]
	v_pk_mul_f32 v[250:251], v[30:31], v[222:223] op_sel:[1,1] op_sel_hi:[1,0] neg_lo:[0,1] neg_hi:[0,1]
	v_pk_fma_f32 v[30:31], v[30:31], v[222:223], v[250:251] op_sel:[0,0,0] op_sel_hi:[0,1,1] neg_lo:[0,1,1] neg_hi:[0,1,0]
	v_pk_mul_f32 v[250:251], v[30:31], v[84:85] op_sel:[1,1] op_sel_hi:[0,1]
	v_pk_fma_f32 v[30:31], v[30:31], v[84:85], v[250:251] op_sel:[0,0,0] op_sel_hi:[1,0,1] neg_hi:[0,0,1]
	v_pk_add_f32 v[242:243], v[6:7], v[22:23]
	v_pk_add_f32 v[244:245], v[6:7], v[22:23] neg_lo:[0,1] neg_hi:[0,1]
	v_pk_add_f32 v[246:247], v[14:15], v[30:31]
	v_pk_add_f32 v[248:249], v[14:15], v[30:31] neg_lo:[0,1] neg_hi:[0,1]
	v_pk_add_f32 v[6:7], v[242:243], v[246:247]
	ds_write_b64 v227, v[6:7] offset:6144
	v_pk_add_f32 v[14:15], v[244:245], v[248:249] op_sel:[0,1] op_sel_hi:[1,0] neg_lo:[0,1]
	ds_write_b64 v227, v[14:15] offset:14336
	v_pk_add_f32 v[22:23], v[242:243], v[246:247] neg_lo:[0,1] neg_hi:[0,1]
	ds_write_b64 v227, v[22:23] offset:22528
	v_pk_add_f32 v[30:31], v[244:245], v[248:249] op_sel:[0,1] op_sel_hi:[1,0] neg_hi:[0,1]
	ds_write_b64 v227, v[30:31] offset:30720
	s_waitcnt lgkmcnt(0)
	s_barrier
	s_mov_b64 s[12:13], -1
	s_and_b64 vcc, exec, s[50:51]
	s_cbranch_vccz .LBB0_1340
; __device__ __forceinline__ float bf2f(u16 h){ return __uint_as_float(((unsigned)h)<<16); }
; HD float2 cmul(float2 a, float2 b){ return make_float2(a.x*b.x - a.y*b.y, a.x*b.y + a.y*b.x); }
; HD float2 cmulc(float2 a, float2 b){ return make_float2(a.x*b.x + a.y*b.y, a.y*b.x - a.x*b.y); }
; HD void inv12_half(const float2* Z, const float2* twA, const float2* twB, int t, float2& x0, float2& x1){
;   float2 w1=cmul(twA[t>>6],twB[t&63]), w2=cmul(w1,w1), w3=cmul(w2,w1);
;   float2 b0=Z[t], b1=cmulc(Z[t+4096],w1), b2=cmulc(Z[t+8192],w2), b3=cmulc(Z[t+12288],w3);
;   float2 s02=make_float2(b0.x+b2.x,b0.y+b2.y), d02=make_float2(b0.x-b2.x,b0.y-b2.y);
;   float2 s13=make_float2(b1.x+b3.x,b1.y+b3.y), d13=make_float2(b1.x-b3.x,b1.y-b3.y);
;   x0=make_float2(s02.x+s13.x,s02.y+s13.y);
;   x1=make_float2(d02.x-d13.y,d02.y+d13.x);
; }
; __device__ __forceinline__ void phase_hyena(KP kp_, int hf){ asm volatile("" : "+s"(kp_)); const Params p=load_params(kp_);
;     ...
;         } else { int tq=tid; asm volatile("" : "+v"(tq));
;           _Pragma("unroll 4") for (int i=0;i<8;++i){ int tb=tq+512*i; float2 xr[2]; inv12_half(Z,twA,twB,tb,xr[0],xr[1]);
;             _Pragma("unroll") for (int hh=0;hh<2;++hh){ int t=tb+hh*4096;
;               float x0=hconv3(r2,t,wb0,wb1,wb2,bb_), x1=hconv3(r2+8192,t,wb0,wb1,wb2,bb_);
;               float2 y=xr[hh]; y.x*=(1.f/16384.f); y.y*=(1.f/16384.f); float2 z1=Zs[t];
;               float o0=x0*(y.x+z1.x*bias1)*bf2f(rz[t]); float o1=x1*(y.y+z1.y*bias1)*bf2f(rz[8192+t]);
;               ybT[(size_t)c*16384+t]=f2bf(o0); ybT[(size_t)c*16384+8192+t]=f2bf(o1); } }
	v_lshlrev_b32_e32 v0, 1, v86
	v_add_u32_e32 v1, 0x1000, v0
	v_add_u32_e32 v2, 0x2000, v0
	v_add_u32_e32 v4, 0x3000, v0
	v_lshlrev_b32_e32 v5, 3, v86
	v_mov_b32_e32 v8, v5
	v_add_u32_e32 v9, 0x10000, v5
	v_lshrrev_b32_e32 v7, 6, v86
	v_lshl_add_u32 v7, v7, 3, s88
	v_and_b32_e32 v108, 63, v86
	v_lshl_add_u32 v108, v108, 3, s91
	ds_read_b64 v[10:11], v108
	s_add_u32 s12, s72, 0x4000
	s_addc_u32 s13, s73, 0
	s_add_u32 s50, s80, 0x8000
	s_addc_u32 s51, s81, 0
	v_mov_b32_e32 v107, 0
	global_load_ushort v228, v0, s[96:97] offset:0
	global_load_ushort v230, v0, s[74:75] offset:0
	global_load_ushort v232, v0, s[72:73] offset:0
	global_load_ushort v234, v0, s[12:13] offset:0
	global_load_ushort v229, v2, s[96:97] offset:0
	global_load_ushort v231, v2, s[74:75] offset:0
	global_load_ushort v233, v2, s[72:73] offset:0
	global_load_ushort v235, v2, s[12:13] offset:0
	v_mov_b32_e32 v6, v5
	global_load_dwordx2 v[236:237], v6, s[80:81] sc1
	global_load_dwordx2 v[238:239], v6, s[50:51] sc1
	ds_read_b64 v[12:13], v7 offset:0
	ds_read_b64 v[14:15], v8 offset:0
	ds_read_b64 v[16:17], v8 offset:32768
	ds_read_b64 v[18:19], v9 offset:0
	ds_read_b64 v[20:21], v9 offset:32768
	global_load_ushort v240, v0, s[96:97] offset:1024
	global_load_ushort v242, v0, s[74:75] offset:1024
	global_load_ushort v244, v0, s[72:73] offset:1024
	global_load_ushort v246, v0, s[12:13] offset:1024
	global_load_ushort v241, v2, s[96:97] offset:1024
	global_load_ushort v243, v2, s[74:75] offset:1024
	global_load_ushort v245, v2, s[72:73] offset:1024
	global_load_ushort v247, v2, s[12:13] offset:1024
	v_add_u32_e32 v6, 0x1000, v5
	global_load_dwordx2 v[248:249], v6, s[80:81] sc1
	global_load_dwordx2 v[250:251], v6, s[50:51] sc1
	ds_read_b64 v[58:59], v7 offset:64
	ds_read_b64 v[60:61], v8 offset:4096
	ds_read_b64 v[62:63], v8 offset:36864
	ds_read_b64 v[64:65], v9 offset:4096
	ds_read_b64 v[66:67], v9 offset:36864
	s_waitcnt lgkmcnt(5)
	v_pk_mul_f32 v[222:223], v[12:13], v[10:11] op_sel:[1,1] op_sel_hi:[1,0]
	v_pk_fma_f32 v[22:23], v[12:13], v[10:11], v[222:223] op_sel:[0,0,0] op_sel_hi:[0,1,1] neg_lo:[0,0,1]
	v_pk_mul_f32 v[222:223], v[22:23], v[22:23] op_sel:[1,1] op_sel_hi:[1,0]
	v_pk_fma_f32 v[24:25], v[22:23], v[22:23], v[222:223] op_sel:[0,0,0] op_sel_hi:[0,1,1] neg_lo:[0,0,1]
	v_pk_mul_f32 v[222:223], v[24:25], v[22:23] op_sel:[1,1] op_sel_hi:[1,0]
	v_pk_fma_f32 v[26:27], v[24:25], v[22:23], v[222:223] op_sel:[0,0,0] op_sel_hi:[0,1,1] neg_lo:[0,0,1]
	v_pk_mul_f32 v[222:223], v[16:17], v[22:23] op_sel:[1,1] op_sel_hi:[0,1]
	v_pk_fma_f32 v[28:29], v[16:17], v[22:23], v[222:223] op_sel:[0,0,0] op_sel_hi:[1,0,1] neg_hi:[0,0,1]
	v_pk_mul_f32 v[222:223], v[18:19], v[24:25] op_sel:[1,1] op_sel_hi:[0,1]
	v_pk_fma_f32 v[30:31], v[18:19], v[24:25], v[222:223] op_sel:[0,0,0] op_sel_hi:[1,0,1] neg_hi:[0,0,1]
	v_pk_mul_f32 v[222:223], v[20:21], v[26:27] op_sel:[1,1] op_sel_hi:[0,1]
	v_pk_fma_f32 v[68:69], v[20:21], v[26:27], v[222:223] op_sel:[0,0,0] op_sel_hi:[1,0,1] neg_hi:[0,0,1]
	v_pk_add_f32 v[70:71], v[14:15], v[30:31]
	v_pk_add_f32 v[72:73], v[14:15], v[30:31] neg_lo:[0,1] neg_hi:[0,1]
	v_pk_add_f32 v[74:75], v[28:29], v[68:69]
	v_pk_add_f32 v[80:81], v[28:29], v[68:69] neg_lo:[0,1] neg_hi:[0,1]
	v_pk_add_f32 v[82:83], v[70:71], v[74:75]
	v_pk_add_f32 v[84:85], v[72:73], v[80:81] op_sel:[0,1] op_sel_hi:[1,0] neg_lo:[0,1]
	s_waitcnt vmcnt(10)
	v_lshlrev_b32_e32 v224, 16, v228
	v_mul_f32_e32 v227, v88, v224
	s_nop 0
	v_fmac_f32_dpp v227, v224, v87 wave_shr:1 row_mask:0xf bank_mask:0xf
	v_fmac_f32_dpp v227, v224, v89 wave_shl:1 row_mask:0xf bank_mask:0xf
	v_add_f32_e32 v94, v90, v227
	v_lshlrev_b32_e32 v224, 16, v230
	v_mul_f32_e32 v227, v88, v224
	s_nop 0
	v_fmac_f32_dpp v227, v224, v87 wave_shr:1 row_mask:0xf bank_mask:0xf
	v_fmac_f32_dpp v227, v224, v89 wave_shl:1 row_mask:0xf bank_mask:0xf
	v_add_f32_e32 v97, v90, v227
	v_lshlrev_b32_e32 v224, 16, v229
	v_mul_f32_e32 v227, v88, v224
	s_nop 0
	v_fmac_f32_dpp v227, v224, v87 wave_shr:1 row_mask:0xf bank_mask:0xf
	v_fmac_f32_dpp v227, v224, v89 wave_shl:1 row_mask:0xf bank_mask:0xf
	v_add_f32_e32 v98, v90, v227
	v_lshlrev_b32_e32 v224, 16, v231
	v_mul_f32_e32 v227, v88, v224
	s_nop 0
	v_fmac_f32_dpp v227, v224, v87 wave_shr:1 row_mask:0xf bank_mask:0xf
	v_fmac_f32_dpp v227, v224, v89 wave_shl:1 row_mask:0xf bank_mask:0xf
	v_add_f32_e32 v100, v90, v227
	v_mul_f32_e32 v108, v91, v236
	v_fmac_f32_e32 v108, 0x38800000, v82
	v_mul_f32_e32 v108, v94, v108
	v_lshlrev_b32_e32 v109, 16, v232
	v_mul_f32_e32 v108, v108, v109
	v_cvt_pk_bf16_f32 v224, v108, v108
	v_mul_f32_e32 v108, v91, v237
	v_fmac_f32_e32 v108, 0x38800000, v83
	v_mul_f32_e32 v108, v108, v97
	v_lshlrev_b32_e32 v109, 16, v234
	v_mul_f32_e32 v108, v108, v109
	v_cvt_pk_bf16_f32 v225, v108, v108
	v_add_u32_e32 v106, 0x0, v0
	v_lshl_add_u64 v[104:105], v[54:55], 0, v[106:107]
	global_store_short v[104:105], v224, off
	v_lshl_add_u64 v[104:105], v[56:57], 0, v[106:107]
	global_store_short v[104:105], v225, off
	v_mul_f32_e32 v108, v91, v238
	v_fmac_f32_e32 v108, 0x38800000, v84
	v_mul_f32_e32 v108, v98, v108
	v_lshlrev_b32_e32 v109, 16, v233
	v_mul_f32_e32 v108, v108, v109
	v_cvt_pk_bf16_f32 v224, v108, v108
	v_mul_f32_e32 v108, v91, v239
	v_fmac_f32_e32 v108, 0x38800000, v85
	v_mul_f32_e32 v108, v108, v100
	v_lshlrev_b32_e32 v109, 16, v235
	v_mul_f32_e32 v108, v108, v109
	v_cvt_pk_bf16_f32 v225, v108, v108
	v_add_u32_e32 v106, 0x0, v2
	v_lshl_add_u64 v[104:105], v[54:55], 0, v[106:107]
	global_store_short v[104:105], v224, off
	v_lshl_add_u64 v[104:105], v[56:57], 0, v[106:107]
	global_store_short v[104:105], v225, off
	global_load_ushort v228, v0, s[96:97] offset:2048
	global_load_ushort v230, v0, s[74:75] offset:2048
	global_load_ushort v232, v0, s[72:73] offset:2048
	global_load_ushort v234, v0, s[12:13] offset:2048
	global_load_ushort v229, v2, s[96:97] offset:2048
	global_load_ushort v231, v2, s[74:75] offset:2048
	global_load_ushort v233, v2, s[72:73] offset:2048
	global_load_ushort v235, v2, s[12:13] offset:2048
	v_add_u32_e32 v6, 0x2000, v5
	global_load_dwordx2 v[236:237], v6, s[80:81] sc1
	global_load_dwordx2 v[238:239], v6, s[50:51] sc1
	ds_read_b64 v[12:13], v7 offset:128
	ds_read_b64 v[14:15], v8 offset:8192
	ds_read_b64 v[16:17], v8 offset:40960
	ds_read_b64 v[18:19], v9 offset:8192
	ds_read_b64 v[20:21], v9 offset:40960
	s_waitcnt lgkmcnt(5)
; __device__ __forceinline__ float bf2f(u16 h){ return __uint_as_float(((unsigned)h)<<16); }
; HD float2 cmul(float2 a, float2 b){ return make_float2(a.x*b.x - a.y*b.y, a.x*b.y + a.y*b.x); }
; HD float2 cmulc(float2 a, float2 b){ return make_float2(a.x*b.x + a.y*b.y, a.y*b.x - a.x*b.y); }
; HD void inv12_half(const float2* Z, const float2* twA, const float2* twB, int t, float2& x0, float2& x1){
;   float2 w1=cmul(twA[t>>6],twB[t&63]), w2=cmul(w1,w1), w3=cmul(w2,w1);
;   float2 b0=Z[t], b1=cmulc(Z[t+4096],w1), b2=cmulc(Z[t+8192],w2), b3=cmulc(Z[t+12288],w3);
;   float2 s02=make_float2(b0.x+b2.x,b0.y+b2.y), d02=make_float2(b0.x-b2.x,b0.y-b2.y);
;   float2 s13=make_float2(b1.x+b3.x,b1.y+b3.y), d13=make_float2(b1.x-b3.x,b1.y-b3.y);
;   x0=make_float2(s02.x+s13.x,s02.y+s13.y);
;   x1=make_float2(d02.x-d13.y,d02.y+d13.x);
; }
; __device__ __forceinline__ void phase_hyena(KP kp_, int hf){ asm volatile("" : "+s"(kp_)); const Params p=load_params(kp_);
;     ...
;         } else { int tq=tid; asm volatile("" : "+v"(tq));
;           _Pragma("unroll 4") for (int i=0;i<8;++i){ int tb=tq+512*i; float2 xr[2]; inv12_half(Z,twA,twB,tb,xr[0],xr[1]);
;             _Pragma("unroll") for (int hh=0;hh<2;++hh){ int t=tb+hh*4096;
;               float x0=hconv3(r2,t,wb0,wb1,wb2,bb_), x1=hconv3(r2+8192,t,wb0,wb1,wb2,bb_);
;               float2 y=xr[hh]; y.x*=(1.f/16384.f); y.y*=(1.f/16384.f); float2 z1=Zs[t];
;               float o0=x0*(y.x+z1.x*bias1)*bf2f(rz[t]); float o1=x1*(y.y+z1.y*bias1)*bf2f(rz[8192+t]);
;               ybT[(size_t)c*16384+t]=f2bf(o0); ybT[(size_t)c*16384+8192+t]=f2bf(o1); } }
	v_pk_mul_f32 v[222:223], v[58:59], v[10:11] op_sel:[1,1] op_sel_hi:[1,0]
	v_pk_fma_f32 v[22:23], v[58:59], v[10:11], v[222:223] op_sel:[0,0,0] op_sel_hi:[0,1,1] neg_lo:[0,0,1]
	v_pk_mul_f32 v[222:223], v[22:23], v[22:23] op_sel:[1,1] op_sel_hi:[1,0]
	v_pk_fma_f32 v[24:25], v[22:23], v[22:23], v[222:223] op_sel:[0,0,0] op_sel_hi:[0,1,1] neg_lo:[0,0,1]
	v_pk_mul_f32 v[222:223], v[24:25], v[22:23] op_sel:[1,1] op_sel_hi:[1,0]
	v_pk_fma_f32 v[26:27], v[24:25], v[22:23], v[222:223] op_sel:[0,0,0] op_sel_hi:[0,1,1] neg_lo:[0,0,1]
	v_pk_mul_f32 v[222:223], v[62:63], v[22:23] op_sel:[1,1] op_sel_hi:[0,1]
	v_pk_fma_f32 v[28:29], v[62:63], v[22:23], v[222:223] op_sel:[0,0,0] op_sel_hi:[1,0,1] neg_hi:[0,0,1]
	v_pk_mul_f32 v[222:223], v[64:65], v[24:25] op_sel:[1,1] op_sel_hi:[0,1]
	v_pk_fma_f32 v[30:31], v[64:65], v[24:25], v[222:223] op_sel:[0,0,0] op_sel_hi:[1,0,1] neg_hi:[0,0,1]
	v_pk_mul_f32 v[222:223], v[66:67], v[26:27] op_sel:[1,1] op_sel_hi:[0,1]
	v_pk_fma_f32 v[68:69], v[66:67], v[26:27], v[222:223] op_sel:[0,0,0] op_sel_hi:[1,0,1] neg_hi:[0,0,1]
	v_pk_add_f32 v[70:71], v[60:61], v[30:31]
	v_pk_add_f32 v[72:73], v[60:61], v[30:31] neg_lo:[0,1] neg_hi:[0,1]
	v_pk_add_f32 v[74:75], v[28:29], v[68:69]
	v_pk_add_f32 v[80:81], v[28:29], v[68:69] neg_lo:[0,1] neg_hi:[0,1]
	v_pk_add_f32 v[82:83], v[70:71], v[74:75]
	v_pk_add_f32 v[84:85], v[72:73], v[80:81] op_sel:[0,1] op_sel_hi:[1,0] neg_lo:[0,1]
	s_waitcnt vmcnt(14)
	v_lshlrev_b32_e32 v224, 16, v240
	v_mul_f32_e32 v227, v88, v224
	s_nop 0
	v_fmac_f32_dpp v227, v224, v87 wave_shr:1 row_mask:0xf bank_mask:0xf
	v_fmac_f32_dpp v227, v224, v89 wave_shl:1 row_mask:0xf bank_mask:0xf
	v_add_f32_e32 v94, v90, v227
	v_lshlrev_b32_e32 v224, 16, v242
	v_mul_f32_e32 v227, v88, v224
	s_nop 0
	v_fmac_f32_dpp v227, v224, v87 wave_shr:1 row_mask:0xf bank_mask:0xf
	v_fmac_f32_dpp v227, v224, v89 wave_shl:1 row_mask:0xf bank_mask:0xf
	v_add_f32_e32 v97, v90, v227
	v_lshlrev_b32_e32 v224, 16, v241
	v_mul_f32_e32 v227, v88, v224
	s_nop 0
	v_fmac_f32_dpp v227, v224, v87 wave_shr:1 row_mask:0xf bank_mask:0xf
	v_fmac_f32_dpp v227, v224, v89 wave_shl:1 row_mask:0xf bank_mask:0xf
	v_add_f32_e32 v98, v90, v227
	v_lshlrev_b32_e32 v224, 16, v243
	v_mul_f32_e32 v227, v88, v224
	s_nop 0
	v_fmac_f32_dpp v227, v224, v87 wave_shr:1 row_mask:0xf bank_mask:0xf
	v_fmac_f32_dpp v227, v224, v89 wave_shl:1 row_mask:0xf bank_mask:0xf
	v_add_f32_e32 v100, v90, v227
	v_mul_f32_e32 v108, v91, v248
	v_fmac_f32_e32 v108, 0x38800000, v82
	v_mul_f32_e32 v108, v94, v108
	v_lshlrev_b32_e32 v109, 16, v244
	v_mul_f32_e32 v108, v108, v109
	v_cvt_pk_bf16_f32 v224, v108, v108
	v_mul_f32_e32 v108, v91, v249
	v_fmac_f32_e32 v108, 0x38800000, v83
	v_mul_f32_e32 v108, v108, v97
	v_lshlrev_b32_e32 v109, 16, v246
	v_mul_f32_e32 v108, v108, v109
	v_cvt_pk_bf16_f32 v225, v108, v108
	v_add_u32_e32 v106, 0x400, v0
	v_lshl_add_u64 v[104:105], v[54:55], 0, v[106:107]
	global_store_short v[104:105], v224, off
	v_lshl_add_u64 v[104:105], v[56:57], 0, v[106:107]
	global_store_short v[104:105], v225, off
	v_mul_f32_e32 v108, v91, v250
	v_fmac_f32_e32 v108, 0x38800000, v84
	v_mul_f32_e32 v108, v98, v108
	v_lshlrev_b32_e32 v109, 16, v245
	v_mul_f32_e32 v108, v108, v109
	v_cvt_pk_bf16_f32 v224, v108, v108
	v_mul_f32_e32 v108, v91, v251
	v_fmac_f32_e32 v108, 0x38800000, v85
	v_mul_f32_e32 v108, v108, v100
	v_lshlrev_b32_e32 v109, 16, v247
	v_mul_f32_e32 v108, v108, v109
	v_cvt_pk_bf16_f32 v225, v108, v108
	v_add_u32_e32 v106, 0x400, v2
	v_lshl_add_u64 v[104:105], v[54:55], 0, v[106:107]
	global_store_short v[104:105], v224, off
	v_lshl_add_u64 v[104:105], v[56:57], 0, v[106:107]
	global_store_short v[104:105], v225, off
	global_load_ushort v240, v0, s[96:97] offset:3072
	global_load_ushort v242, v0, s[74:75] offset:3072
	global_load_ushort v244, v0, s[72:73] offset:3072
	global_load_ushort v246, v0, s[12:13] offset:3072
	global_load_ushort v241, v2, s[96:97] offset:3072
	global_load_ushort v243, v2, s[74:75] offset:3072
	global_load_ushort v245, v2, s[72:73] offset:3072
	global_load_ushort v247, v2, s[12:13] offset:3072
	v_add_u32_e32 v6, 0x3000, v5
	global_load_dwordx2 v[248:249], v6, s[80:81] sc1
	global_load_dwordx2 v[250:251], v6, s[50:51] sc1
	ds_read_b64 v[58:59], v7 offset:192
	ds_read_b64 v[60:61], v8 offset:12288
	ds_read_b64 v[62:63], v8 offset:45056
	ds_read_b64 v[64:65], v9 offset:12288
	ds_read_b64 v[66:67], v9 offset:45056
	s_waitcnt lgkmcnt(5)
	v_pk_mul_f32 v[222:223], v[12:13], v[10:11] op_sel:[1,1] op_sel_hi:[1,0]
	v_pk_fma_f32 v[22:23], v[12:13], v[10:11], v[222:223] op_sel:[0,0,0] op_sel_hi:[0,1,1] neg_lo:[0,0,1]
	v_pk_mul_f32 v[222:223], v[22:23], v[22:23] op_sel:[1,1] op_sel_hi:[1,0]
	v_pk_fma_f32 v[24:25], v[22:23], v[22:23], v[222:223] op_sel:[0,0,0] op_sel_hi:[0,1,1] neg_lo:[0,0,1]
	v_pk_mul_f32 v[222:223], v[24:25], v[22:23] op_sel:[1,1] op_sel_hi:[1,0]
	v_pk_fma_f32 v[26:27], v[24:25], v[22:23], v[222:223] op_sel:[0,0,0] op_sel_hi:[0,1,1] neg_lo:[0,0,1]
	v_pk_mul_f32 v[222:223], v[16:17], v[22:23] op_sel:[1,1] op_sel_hi:[0,1]
	v_pk_fma_f32 v[28:29], v[16:17], v[22:23], v[222:223] op_sel:[0,0,0] op_sel_hi:[1,0,1] neg_hi:[0,0,1]
	v_pk_mul_f32 v[222:223], v[18:19], v[24:25] op_sel:[1,1] op_sel_hi:[0,1]
	v_pk_fma_f32 v[30:31], v[18:19], v[24:25], v[222:223] op_sel:[0,0,0] op_sel_hi:[1,0,1] neg_hi:[0,0,1]
	v_pk_mul_f32 v[222:223], v[20:21], v[26:27] op_sel:[1,1] op_sel_hi:[0,1]
	v_pk_fma_f32 v[68:69], v[20:21], v[26:27], v[222:223] op_sel:[0,0,0] op_sel_hi:[1,0,1] neg_hi:[0,0,1]
	v_pk_add_f32 v[70:71], v[14:15], v[30:31]
	v_pk_add_f32 v[72:73], v[14:15], v[30:31] neg_lo:[0,1] neg_hi:[0,1]
	v_pk_add_f32 v[74:75], v[28:29], v[68:69]
	v_pk_add_f32 v[80:81], v[28:29], v[68:69] neg_lo:[0,1] neg_hi:[0,1]
	v_pk_add_f32 v[82:83], v[70:71], v[74:75]
	v_pk_add_f32 v[84:85], v[72:73], v[80:81] op_sel:[0,1] op_sel_hi:[1,0] neg_lo:[0,1]
	s_waitcnt vmcnt(14)
; __device__ __forceinline__ float bf2f(u16 h){ return __uint_as_float(((unsigned)h)<<16); }
; HD float2 cmul(float2 a, float2 b){ return make_float2(a.x*b.x - a.y*b.y, a.x*b.y + a.y*b.x); }
; HD float2 cmulc(float2 a, float2 b){ return make_float2(a.x*b.x + a.y*b.y, a.y*b.x - a.x*b.y); }
; HD void inv12_half(const float2* Z, const float2* twA, const float2* twB, int t, float2& x0, float2& x1){
;   float2 w1=cmul(twA[t>>6],twB[t&63]), w2=cmul(w1,w1), w3=cmul(w2,w1);
;   float2 b0=Z[t], b1=cmulc(Z[t+4096],w1), b2=cmulc(Z[t+8192],w2), b3=cmulc(Z[t+12288],w3);
;   float2 s02=make_float2(b0.x+b2.x,b0.y+b2.y), d02=make_float2(b0.x-b2.x,b0.y-b2.y);
;   float2 s13=make_float2(b1.x+b3.x,b1.y+b3.y), d13=make_float2(b1.x-b3.x,b1.y-b3.y);
;   x0=make_float2(s02.x+s13.x,s02.y+s13.y);
;   x1=make_float2(d02.x-d13.y,d02.y+d13.x);
; }
; __device__ __forceinline__ void phase_hyena(KP kp_, int hf){ asm volatile("" : "+s"(kp_)); const Params p=load_params(kp_);
;     ...
;         } else { int tq=tid; asm volatile("" : "+v"(tq));
;           _Pragma("unroll 4") for (int i=0;i<8;++i){ int tb=tq+512*i; float2 xr[2]; inv12_half(Z,twA,twB,tb,xr[0],xr[1]);
;             _Pragma("unroll") for (int hh=0;hh<2;++hh){ int t=tb+hh*4096;
;               float x0=hconv3(r2,t,wb0,wb1,wb2,bb_), x1=hconv3(r2+8192,t,wb0,wb1,wb2,bb_);
;               float2 y=xr[hh]; y.x*=(1.f/16384.f); y.y*=(1.f/16384.f); float2 z1=Zs[t];
;               float o0=x0*(y.x+z1.x*bias1)*bf2f(rz[t]); float o1=x1*(y.y+z1.y*bias1)*bf2f(rz[8192+t]);
;               ybT[(size_t)c*16384+t]=f2bf(o0); ybT[(size_t)c*16384+8192+t]=f2bf(o1); } }
	v_lshlrev_b32_e32 v224, 16, v228
	v_mul_f32_e32 v227, v88, v224
	s_nop 0
	v_fmac_f32_dpp v227, v224, v87 wave_shr:1 row_mask:0xf bank_mask:0xf
	v_fmac_f32_dpp v227, v224, v89 wave_shl:1 row_mask:0xf bank_mask:0xf
	v_add_f32_e32 v94, v90, v227
	v_lshlrev_b32_e32 v224, 16, v230
	v_mul_f32_e32 v227, v88, v224
	s_nop 0
	v_fmac_f32_dpp v227, v224, v87 wave_shr:1 row_mask:0xf bank_mask:0xf
	v_fmac_f32_dpp v227, v224, v89 wave_shl:1 row_mask:0xf bank_mask:0xf
	v_add_f32_e32 v97, v90, v227
	v_lshlrev_b32_e32 v224, 16, v229
	v_mul_f32_e32 v227, v88, v224
	s_nop 0
	v_fmac_f32_dpp v227, v224, v87 wave_shr:1 row_mask:0xf bank_mask:0xf
	v_fmac_f32_dpp v227, v224, v89 wave_shl:1 row_mask:0xf bank_mask:0xf
	v_add_f32_e32 v98, v90, v227
	v_lshlrev_b32_e32 v224, 16, v231
	v_mul_f32_e32 v227, v88, v224
	s_nop 0
	v_fmac_f32_dpp v227, v224, v87 wave_shr:1 row_mask:0xf bank_mask:0xf
	v_fmac_f32_dpp v227, v224, v89 wave_shl:1 row_mask:0xf bank_mask:0xf
	v_add_f32_e32 v100, v90, v227
	v_mul_f32_e32 v108, v91, v236
	v_fmac_f32_e32 v108, 0x38800000, v82
	v_mul_f32_e32 v108, v94, v108
	v_lshlrev_b32_e32 v109, 16, v232
	v_mul_f32_e32 v108, v108, v109
	v_cvt_pk_bf16_f32 v224, v108, v108
	v_mul_f32_e32 v108, v91, v237
	v_fmac_f32_e32 v108, 0x38800000, v83
	v_mul_f32_e32 v108, v108, v97
	v_lshlrev_b32_e32 v109, 16, v234
	v_mul_f32_e32 v108, v108, v109
	v_cvt_pk_bf16_f32 v225, v108, v108
	v_add_u32_e32 v106, 0x800, v0
	v_lshl_add_u64 v[104:105], v[54:55], 0, v[106:107]
	global_store_short v[104:105], v224, off
	v_lshl_add_u64 v[104:105], v[56:57], 0, v[106:107]
	global_store_short v[104:105], v225, off
	v_mul_f32_e32 v108, v91, v238
	v_fmac_f32_e32 v108, 0x38800000, v84
	v_mul_f32_e32 v108, v98, v108
	v_lshlrev_b32_e32 v109, 16, v233
	v_mul_f32_e32 v108, v108, v109
	v_cvt_pk_bf16_f32 v224, v108, v108
	v_mul_f32_e32 v108, v91, v239
	v_fmac_f32_e32 v108, 0x38800000, v85
	v_mul_f32_e32 v108, v108, v100
	v_lshlrev_b32_e32 v109, 16, v235
	v_mul_f32_e32 v108, v108, v109
	v_cvt_pk_bf16_f32 v225, v108, v108
	v_add_u32_e32 v106, 0x800, v2
	v_lshl_add_u64 v[104:105], v[54:55], 0, v[106:107]
	global_store_short v[104:105], v224, off
	v_lshl_add_u64 v[104:105], v[56:57], 0, v[106:107]
	global_store_short v[104:105], v225, off
	global_load_ushort v228, v1, s[96:97] offset:0
	global_load_ushort v230, v1, s[74:75] offset:0
	global_load_ushort v232, v1, s[72:73] offset:0
	global_load_ushort v234, v1, s[12:13] offset:0
	global_load_ushort v229, v4, s[96:97] offset:0
	global_load_ushort v231, v4, s[74:75] offset:0
	global_load_ushort v233, v4, s[72:73] offset:0
	global_load_ushort v235, v4, s[12:13] offset:0
	v_add_u32_e32 v6, 0x4000, v5
	global_load_dwordx2 v[236:237], v6, s[80:81] sc1
	global_load_dwordx2 v[238:239], v6, s[50:51] sc1
	ds_read_b64 v[12:13], v7 offset:256
	ds_read_b64 v[14:15], v8 offset:16384
	ds_read_b64 v[16:17], v8 offset:49152
	ds_read_b64 v[18:19], v9 offset:16384
	ds_read_b64 v[20:21], v9 offset:49152
	s_waitcnt lgkmcnt(5)
	v_pk_mul_f32 v[222:223], v[58:59], v[10:11] op_sel:[1,1] op_sel_hi:[1,0]
	v_pk_fma_f32 v[22:23], v[58:59], v[10:11], v[222:223] op_sel:[0,0,0] op_sel_hi:[0,1,1] neg_lo:[0,0,1]
	v_pk_mul_f32 v[222:223], v[22:23], v[22:23] op_sel:[1,1] op_sel_hi:[1,0]
	v_pk_fma_f32 v[24:25], v[22:23], v[22:23], v[222:223] op_sel:[0,0,0] op_sel_hi:[0,1,1] neg_lo:[0,0,1]
	v_pk_mul_f32 v[222:223], v[24:25], v[22:23] op_sel:[1,1] op_sel_hi:[1,0]
	v_pk_fma_f32 v[26:27], v[24:25], v[22:23], v[222:223] op_sel:[0,0,0] op_sel_hi:[0,1,1] neg_lo:[0,0,1]
	v_pk_mul_f32 v[222:223], v[62:63], v[22:23] op_sel:[1,1] op_sel_hi:[0,1]
	v_pk_fma_f32 v[28:29], v[62:63], v[22:23], v[222:223] op_sel:[0,0,0] op_sel_hi:[1,0,1] neg_hi:[0,0,1]
	v_pk_mul_f32 v[222:223], v[64:65], v[24:25] op_sel:[1,1] op_sel_hi:[0,1]
	v_pk_fma_f32 v[30:31], v[64:65], v[24:25], v[222:223] op_sel:[0,0,0] op_sel_hi:[1,0,1] neg_hi:[0,0,1]
	v_pk_mul_f32 v[222:223], v[66:67], v[26:27] op_sel:[1,1] op_sel_hi:[0,1]
	v_pk_fma_f32 v[68:69], v[66:67], v[26:27], v[222:223] op_sel:[0,0,0] op_sel_hi:[1,0,1] neg_hi:[0,0,1]
	v_pk_add_f32 v[70:71], v[60:61], v[30:31]
	v_pk_add_f32 v[72:73], v[60:61], v[30:31] neg_lo:[0,1] neg_hi:[0,1]
	v_pk_add_f32 v[74:75], v[28:29], v[68:69]
	v_pk_add_f32 v[80:81], v[28:29], v[68:69] neg_lo:[0,1] neg_hi:[0,1]
	v_pk_add_f32 v[82:83], v[70:71], v[74:75]
	v_pk_add_f32 v[84:85], v[72:73], v[80:81] op_sel:[0,1] op_sel_hi:[1,0] neg_lo:[0,1]
	s_waitcnt vmcnt(14)
; __device__ __forceinline__ float bf2f(u16 h){ return __uint_as_float(((unsigned)h)<<16); }
; HD float2 cmul(float2 a, float2 b){ return make_float2(a.x*b.x - a.y*b.y, a.x*b.y + a.y*b.x); }
; HD float2 cmulc(float2 a, float2 b){ return make_float2(a.x*b.x + a.y*b.y, a.y*b.x - a.x*b.y); }
; HD void inv12_half(const float2* Z, const float2* twA, const float2* twB, int t, float2& x0, float2& x1){
;   float2 w1=cmul(twA[t>>6],twB[t&63]), w2=cmul(w1,w1), w3=cmul(w2,w1);
;   float2 b0=Z[t], b1=cmulc(Z[t+4096],w1), b2=cmulc(Z[t+8192],w2), b3=cmulc(Z[t+12288],w3);
;   float2 s02=make_float2(b0.x+b2.x,b0.y+b2.y), d02=make_float2(b0.x-b2.x,b0.y-b2.y);
;   float2 s13=make_float2(b1.x+b3.x,b1.y+b3.y), d13=make_float2(b1.x-b3.x,b1.y-b3.y);
;   x0=make_float2(s02.x+s13.x,s02.y+s13.y);
;   x1=make_float2(d02.x-d13.y,d02.y+d13.x);
; }
; __device__ __forceinline__ void phase_hyena(KP kp_, int hf){ asm volatile("" : "+s"(kp_)); const Params p=load_params(kp_);
;     ...
;         } else { int tq=tid; asm volatile("" : "+v"(tq));
;           _Pragma("unroll 4") for (int i=0;i<8;++i){ int tb=tq+512*i; float2 xr[2]; inv12_half(Z,twA,twB,tb,xr[0],xr[1]);
;             _Pragma("unroll") for (int hh=0;hh<2;++hh){ int t=tb+hh*4096;
;               float x0=hconv3(r2,t,wb0,wb1,wb2,bb_), x1=hconv3(r2+8192,t,wb0,wb1,wb2,bb_);
;               float2 y=xr[hh]; y.x*=(1.f/16384.f); y.y*=(1.f/16384.f); float2 z1=Zs[t];
;               float o0=x0*(y.x+z1.x*bias1)*bf2f(rz[t]); float o1=x1*(y.y+z1.y*bias1)*bf2f(rz[8192+t]);
;               ybT[(size_t)c*16384+t]=f2bf(o0); ybT[(size_t)c*16384+8192+t]=f2bf(o1); } }
	v_lshlrev_b32_e32 v224, 16, v240
	v_mul_f32_e32 v227, v88, v224
	s_nop 0
	v_fmac_f32_dpp v227, v224, v87 wave_shr:1 row_mask:0xf bank_mask:0xf
	v_fmac_f32_dpp v227, v224, v89 wave_shl:1 row_mask:0xf bank_mask:0xf
	v_add_f32_e32 v94, v90, v227
	v_lshlrev_b32_e32 v224, 16, v242
	v_mul_f32_e32 v227, v88, v224
	s_nop 0
	v_fmac_f32_dpp v227, v224, v87 wave_shr:1 row_mask:0xf bank_mask:0xf
	v_fmac_f32_dpp v227, v224, v89 wave_shl:1 row_mask:0xf bank_mask:0xf
	v_add_f32_e32 v97, v90, v227
	v_lshlrev_b32_e32 v224, 16, v241
	v_mul_f32_e32 v227, v88, v224
	s_nop 0
	v_fmac_f32_dpp v227, v224, v87 wave_shr:1 row_mask:0xf bank_mask:0xf
	v_fmac_f32_dpp v227, v224, v89 wave_shl:1 row_mask:0xf bank_mask:0xf
	v_add_f32_e32 v98, v90, v227
	v_lshlrev_b32_e32 v224, 16, v243
	v_mul_f32_e32 v227, v88, v224
	s_nop 0
	v_fmac_f32_dpp v227, v224, v87 wave_shr:1 row_mask:0xf bank_mask:0xf
	v_fmac_f32_dpp v227, v224, v89 wave_shl:1 row_mask:0xf bank_mask:0xf
	v_add_f32_e32 v100, v90, v227
	v_mul_f32_e32 v108, v91, v248
	v_fmac_f32_e32 v108, 0x38800000, v82
	v_mul_f32_e32 v108, v94, v108
	v_lshlrev_b32_e32 v109, 16, v244
	v_mul_f32_e32 v108, v108, v109
	v_cvt_pk_bf16_f32 v224, v108, v108
	v_mul_f32_e32 v108, v91, v249
	v_fmac_f32_e32 v108, 0x38800000, v83
	v_mul_f32_e32 v108, v108, v97
	v_lshlrev_b32_e32 v109, 16, v246
	v_mul_f32_e32 v108, v108, v109
	v_cvt_pk_bf16_f32 v225, v108, v108
	v_add_u32_e32 v106, 0xc00, v0
	v_lshl_add_u64 v[104:105], v[54:55], 0, v[106:107]
	global_store_short v[104:105], v224, off
	v_lshl_add_u64 v[104:105], v[56:57], 0, v[106:107]
	global_store_short v[104:105], v225, off
	v_mul_f32_e32 v108, v91, v250
	v_fmac_f32_e32 v108, 0x38800000, v84
	v_mul_f32_e32 v108, v98, v108
	v_lshlrev_b32_e32 v109, 16, v245
	v_mul_f32_e32 v108, v108, v109
	v_cvt_pk_bf16_f32 v224, v108, v108
	v_mul_f32_e32 v108, v91, v251
	v_fmac_f32_e32 v108, 0x38800000, v85
	v_mul_f32_e32 v108, v108, v100
	v_lshlrev_b32_e32 v109, 16, v247
	v_mul_f32_e32 v108, v108, v109
	v_cvt_pk_bf16_f32 v225, v108, v108
	v_add_u32_e32 v106, 0xc00, v2
	v_lshl_add_u64 v[104:105], v[54:55], 0, v[106:107]
	global_store_short v[104:105], v224, off
	v_lshl_add_u64 v[104:105], v[56:57], 0, v[106:107]
	global_store_short v[104:105], v225, off
	global_load_ushort v240, v1, s[96:97] offset:1024
	global_load_ushort v242, v1, s[74:75] offset:1024
	global_load_ushort v244, v1, s[72:73] offset:1024
	global_load_ushort v246, v1, s[12:13] offset:1024
	global_load_ushort v241, v4, s[96:97] offset:1024
	global_load_ushort v243, v4, s[74:75] offset:1024
	global_load_ushort v245, v4, s[72:73] offset:1024
	global_load_ushort v247, v4, s[12:13] offset:1024
	v_add_u32_e32 v6, 0x5000, v5
	global_load_dwordx2 v[248:249], v6, s[80:81] sc1
	global_load_dwordx2 v[250:251], v6, s[50:51] sc1
	ds_read_b64 v[58:59], v7 offset:320
	ds_read_b64 v[60:61], v8 offset:20480
	ds_read_b64 v[62:63], v8 offset:53248
	ds_read_b64 v[64:65], v9 offset:20480
	ds_read_b64 v[66:67], v9 offset:53248
	s_waitcnt lgkmcnt(5)
	v_pk_mul_f32 v[222:223], v[12:13], v[10:11] op_sel:[1,1] op_sel_hi:[1,0]
	v_pk_fma_f32 v[22:23], v[12:13], v[10:11], v[222:223] op_sel:[0,0,0] op_sel_hi:[0,1,1] neg_lo:[0,0,1]
	v_pk_mul_f32 v[222:223], v[22:23], v[22:23] op_sel:[1,1] op_sel_hi:[1,0]
	v_pk_fma_f32 v[24:25], v[22:23], v[22:23], v[222:223] op_sel:[0,0,0] op_sel_hi:[0,1,1] neg_lo:[0,0,1]
	v_pk_mul_f32 v[222:223], v[24:25], v[22:23] op_sel:[1,1] op_sel_hi:[1,0]
	v_pk_fma_f32 v[26:27], v[24:25], v[22:23], v[222:223] op_sel:[0,0,0] op_sel_hi:[0,1,1] neg_lo:[0,0,1]
	v_pk_mul_f32 v[222:223], v[16:17], v[22:23] op_sel:[1,1] op_sel_hi:[0,1]
	v_pk_fma_f32 v[28:29], v[16:17], v[22:23], v[222:223] op_sel:[0,0,0] op_sel_hi:[1,0,1] neg_hi:[0,0,1]
	v_pk_mul_f32 v[222:223], v[18:19], v[24:25] op_sel:[1,1] op_sel_hi:[0,1]
	v_pk_fma_f32 v[30:31], v[18:19], v[24:25], v[222:223] op_sel:[0,0,0] op_sel_hi:[1,0,1] neg_hi:[0,0,1]
	v_pk_mul_f32 v[222:223], v[20:21], v[26:27] op_sel:[1,1] op_sel_hi:[0,1]
	v_pk_fma_f32 v[68:69], v[20:21], v[26:27], v[222:223] op_sel:[0,0,0] op_sel_hi:[1,0,1] neg_hi:[0,0,1]
	v_pk_add_f32 v[70:71], v[14:15], v[30:31]
	v_pk_add_f32 v[72:73], v[14:15], v[30:31] neg_lo:[0,1] neg_hi:[0,1]
	v_pk_add_f32 v[74:75], v[28:29], v[68:69]
	v_pk_add_f32 v[80:81], v[28:29], v[68:69] neg_lo:[0,1] neg_hi:[0,1]
	v_pk_add_f32 v[82:83], v[70:71], v[74:75]
	v_pk_add_f32 v[84:85], v[72:73], v[80:81] op_sel:[0,1] op_sel_hi:[1,0] neg_lo:[0,1]
	s_waitcnt vmcnt(14)
; __device__ __forceinline__ float bf2f(u16 h){ return __uint_as_float(((unsigned)h)<<16); }
; __device__ __forceinline__ float hconv3(const u16* __restrict__ row, int t, float w0, float w1, float w2, float bias){
;   float m = bf2f(row[t]);
;   int mi=__float_as_int(m);
;   float l=__int_as_float(__builtin_amdgcn_update_dpp(0, mi, 0x138, 0xf, 0xf, false));
;   float r=__int_as_float(__builtin_amdgcn_update_dpp(0, mi, 0x130, 0xf, 0xf, false));
;   return w0*l+w1*m+w2*r+bias;
; __device__ __forceinline__ void phase_hyena(KP kp_, int hf){ asm volatile("" : "+s"(kp_)); const Params p=load_params(kp_);
;     ...
;           _Pragma("unroll 4") for (int i=0;i<8;++i){ int tb=tq+512*i; float2 xr[2]; inv12_half(Z,twA,twB,tb,xr[0],xr[1]);
;             _Pragma("unroll") for (int hh=0;hh<2;++hh){ int t=tb+hh*4096;
;               float x0=hconv3(r2,t,wb0,wb1,wb2,bb_), x1=hconv3(r2+8192,t,wb0,wb1,wb2,bb_);
;               float2 y=xr[hh]; y.x*=(1.f/16384.f); y.y*=(1.f/16384.f); float2 z1=Zs[t];
;               float o0=x0*(y.x+z1.x*bias1)*bf2f(rz[t]); float o1=x1*(y.y+z1.y*bias1)*bf2f(rz[8192+t]);
;               ybT[(size_t)c*16384+t]=f2bf(o0); ybT[(size_t)c*16384+8192+t]=f2bf(o1); } }
	v_lshlrev_b32_e32 v224, 16, v228
	v_mul_f32_e32 v227, v88, v224
	s_nop 0
	v_fmac_f32_dpp v227, v224, v87 wave_shr:1 row_mask:0xf bank_mask:0xf
	v_fmac_f32_dpp v227, v224, v89 wave_shl:1 row_mask:0xf bank_mask:0xf
	v_add_f32_e32 v94, v90, v227
	v_lshlrev_b32_e32 v224, 16, v230
	v_mul_f32_e32 v227, v88, v224
	s_nop 0
	v_fmac_f32_dpp v227, v224, v87 wave_shr:1 row_mask:0xf bank_mask:0xf
	v_fmac_f32_dpp v227, v224, v89 wave_shl:1 row_mask:0xf bank_mask:0xf
	v_add_f32_e32 v97, v90, v227
	v_lshlrev_b32_e32 v224, 16, v229
	v_mul_f32_e32 v227, v88, v224
	s_nop 0
	v_fmac_f32_dpp v227, v224, v87 wave_shr:1 row_mask:0xf bank_mask:0xf
	v_fmac_f32_dpp v227, v224, v89 wave_shl:1 row_mask:0xf bank_mask:0xf
	v_add_f32_e32 v98, v90, v227
	v_lshlrev_b32_e32 v224, 16, v231
	v_mul_f32_e32 v227, v88, v224
	s_nop 0
	v_fmac_f32_dpp v227, v224, v87 wave_shr:1 row_mask:0xf bank_mask:0xf
	v_fmac_f32_dpp v227, v224, v89 wave_shl:1 row_mask:0xf bank_mask:0xf
	v_add_f32_e32 v100, v90, v227
	v_mul_f32_e32 v108, v91, v236
	v_fmac_f32_e32 v108, 0x38800000, v82
	v_mul_f32_e32 v108, v94, v108
	v_lshlrev_b32_e32 v109, 16, v232
	v_mul_f32_e32 v108, v108, v109
	v_cvt_pk_bf16_f32 v224, v108, v108
	v_mul_f32_e32 v108, v91, v237
	v_fmac_f32_e32 v108, 0x38800000, v83
	v_mul_f32_e32 v108, v108, v97
	v_lshlrev_b32_e32 v109, 16, v234
	v_mul_f32_e32 v108, v108, v109
	v_cvt_pk_bf16_f32 v225, v108, v108
	v_add_u32_e32 v106, 0x0, v1
	v_lshl_add_u64 v[104:105], v[54:55], 0, v[106:107]
	global_store_short v[104:105], v224, off
	v_lshl_add_u64 v[104:105], v[56:57], 0, v[106:107]
	global_store_short v[104:105], v225, off
	v_mul_f32_e32 v108, v91, v238
	v_fmac_f32_e32 v108, 0x38800000, v84
	v_mul_f32_e32 v108, v98, v108
	v_lshlrev_b32_e32 v109, 16, v233
	v_mul_f32_e32 v108, v108, v109
	v_cvt_pk_bf16_f32 v224, v108, v108
	v_mul_f32_e32 v108, v91, v239
	v_fmac_f32_e32 v108, 0x38800000, v85
	v_mul_f32_e32 v108, v108, v100
	v_lshlrev_b32_e32 v109, 16, v235
	v_mul_f32_e32 v108, v108, v109
	v_cvt_pk_bf16_f32 v225, v108, v108
	v_add_u32_e32 v106, 0x0, v4
	v_lshl_add_u64 v[104:105], v[54:55], 0, v[106:107]
	global_store_short v[104:105], v224, off
	v_lshl_add_u64 v[104:105], v[56:57], 0, v[106:107]
	global_store_short v[104:105], v225, off
	global_load_ushort v228, v1, s[96:97] offset:2048
	global_load_ushort v230, v1, s[74:75] offset:2048
	global_load_ushort v232, v1, s[72:73] offset:2048
	global_load_ushort v234, v1, s[12:13] offset:2048
	global_load_ushort v229, v4, s[96:97] offset:2048
	global_load_ushort v231, v4, s[74:75] offset:2048
	global_load_ushort v233, v4, s[72:73] offset:2048
	global_load_ushort v235, v4, s[12:13] offset:2048
	v_add_u32_e32 v6, 0x6000, v5
	global_load_dwordx2 v[236:237], v6, s[80:81] sc1
	global_load_dwordx2 v[238:239], v6, s[50:51] sc1
	ds_read_b64 v[12:13], v7 offset:384
	ds_read_b64 v[14:15], v8 offset:24576
	ds_read_b64 v[16:17], v8 offset:57344
	ds_read_b64 v[18:19], v9 offset:24576
	ds_read_b64 v[20:21], v9 offset:57344
	s_waitcnt lgkmcnt(5)
	v_pk_mul_f32 v[222:223], v[58:59], v[10:11] op_sel:[1,1] op_sel_hi:[1,0]
	v_pk_fma_f32 v[22:23], v[58:59], v[10:11], v[222:223] op_sel:[0,0,0] op_sel_hi:[0,1,1] neg_lo:[0,0,1]
	v_pk_mul_f32 v[222:223], v[22:23], v[22:23] op_sel:[1,1] op_sel_hi:[1,0]
	v_pk_fma_f32 v[24:25], v[22:23], v[22:23], v[222:223] op_sel:[0,0,0] op_sel_hi:[0,1,1] neg_lo:[0,0,1]
	v_pk_mul_f32 v[222:223], v[24:25], v[22:23] op_sel:[1,1] op_sel_hi:[1,0]
	v_pk_fma_f32 v[26:27], v[24:25], v[22:23], v[222:223] op_sel:[0,0,0] op_sel_hi:[0,1,1] neg_lo:[0,0,1]
	v_pk_mul_f32 v[222:223], v[62:63], v[22:23] op_sel:[1,1] op_sel_hi:[0,1]
	v_pk_fma_f32 v[28:29], v[62:63], v[22:23], v[222:223] op_sel:[0,0,0] op_sel_hi:[1,0,1] neg_hi:[0,0,1]
	v_pk_mul_f32 v[222:223], v[64:65], v[24:25] op_sel:[1,1] op_sel_hi:[0,1]
	v_pk_fma_f32 v[30:31], v[64:65], v[24:25], v[222:223] op_sel:[0,0,0] op_sel_hi:[1,0,1] neg_hi:[0,0,1]
	v_pk_mul_f32 v[222:223], v[66:67], v[26:27] op_sel:[1,1] op_sel_hi:[0,1]
	v_pk_fma_f32 v[68:69], v[66:67], v[26:27], v[222:223] op_sel:[0,0,0] op_sel_hi:[1,0,1] neg_hi:[0,0,1]
	v_pk_add_f32 v[70:71], v[60:61], v[30:31]
	v_pk_add_f32 v[72:73], v[60:61], v[30:31] neg_lo:[0,1] neg_hi:[0,1]
	v_pk_add_f32 v[74:75], v[28:29], v[68:69]
	v_pk_add_f32 v[80:81], v[28:29], v[68:69] neg_lo:[0,1] neg_hi:[0,1]
	v_pk_add_f32 v[82:83], v[70:71], v[74:75]
	v_pk_add_f32 v[84:85], v[72:73], v[80:81] op_sel:[0,1] op_sel_hi:[1,0] neg_lo:[0,1]
	s_waitcnt vmcnt(14)
; __device__ __forceinline__ float bf2f(u16 h){ return __uint_as_float(((unsigned)h)<<16); }
; __device__ __forceinline__ float hconv3(const u16* __restrict__ row, int t, float w0, float w1, float w2, float bias){
;   float m = bf2f(row[t]);
;   int mi=__float_as_int(m);
;   float l=__int_as_float(__builtin_amdgcn_update_dpp(0, mi, 0x138, 0xf, 0xf, false));
;   float r=__int_as_float(__builtin_amdgcn_update_dpp(0, mi, 0x130, 0xf, 0xf, false));
;   return w0*l+w1*m+w2*r+bias;
; __device__ __forceinline__ void phase_hyena(KP kp_, int hf){ asm volatile("" : "+s"(kp_)); const Params p=load_params(kp_);
;     ...
;           _Pragma("unroll 4") for (int i=0;i<8;++i){ int tb=tq+512*i; float2 xr[2]; inv12_half(Z,twA,twB,tb,xr[0],xr[1]);
;             _Pragma("unroll") for (int hh=0;hh<2;++hh){ int t=tb+hh*4096;
;               float x0=hconv3(r2,t,wb0,wb1,wb2,bb_), x1=hconv3(r2+8192,t,wb0,wb1,wb2,bb_);
;               float2 y=xr[hh]; y.x*=(1.f/16384.f); y.y*=(1.f/16384.f); float2 z1=Zs[t];
;               float o0=x0*(y.x+z1.x*bias1)*bf2f(rz[t]); float o1=x1*(y.y+z1.y*bias1)*bf2f(rz[8192+t]);
;               ybT[(size_t)c*16384+t]=f2bf(o0); ybT[(size_t)c*16384+8192+t]=f2bf(o1); } }
	v_lshlrev_b32_e32 v224, 16, v240
	v_mul_f32_e32 v227, v88, v224
	s_nop 0
	v_fmac_f32_dpp v227, v224, v87 wave_shr:1 row_mask:0xf bank_mask:0xf
	v_fmac_f32_dpp v227, v224, v89 wave_shl:1 row_mask:0xf bank_mask:0xf
	v_add_f32_e32 v94, v90, v227
	v_lshlrev_b32_e32 v224, 16, v242
	v_mul_f32_e32 v227, v88, v224
	s_nop 0
	v_fmac_f32_dpp v227, v224, v87 wave_shr:1 row_mask:0xf bank_mask:0xf
	v_fmac_f32_dpp v227, v224, v89 wave_shl:1 row_mask:0xf bank_mask:0xf
	v_add_f32_e32 v97, v90, v227
	v_lshlrev_b32_e32 v224, 16, v241
	v_mul_f32_e32 v227, v88, v224
	s_nop 0
	v_fmac_f32_dpp v227, v224, v87 wave_shr:1 row_mask:0xf bank_mask:0xf
	v_fmac_f32_dpp v227, v224, v89 wave_shl:1 row_mask:0xf bank_mask:0xf
	v_add_f32_e32 v98, v90, v227
	v_lshlrev_b32_e32 v224, 16, v243
	v_mul_f32_e32 v227, v88, v224
	s_nop 0
	v_fmac_f32_dpp v227, v224, v87 wave_shr:1 row_mask:0xf bank_mask:0xf
	v_fmac_f32_dpp v227, v224, v89 wave_shl:1 row_mask:0xf bank_mask:0xf
	v_add_f32_e32 v100, v90, v227
	v_mul_f32_e32 v108, v91, v248
	v_fmac_f32_e32 v108, 0x38800000, v82
	v_mul_f32_e32 v108, v94, v108
	v_lshlrev_b32_e32 v109, 16, v244
	v_mul_f32_e32 v108, v108, v109
	v_cvt_pk_bf16_f32 v224, v108, v108
	v_mul_f32_e32 v108, v91, v249
	v_fmac_f32_e32 v108, 0x38800000, v83
	v_mul_f32_e32 v108, v108, v97
	v_lshlrev_b32_e32 v109, 16, v246
	v_mul_f32_e32 v108, v108, v109
	v_cvt_pk_bf16_f32 v225, v108, v108
	v_add_u32_e32 v106, 0x400, v1
	v_lshl_add_u64 v[104:105], v[54:55], 0, v[106:107]
	global_store_short v[104:105], v224, off
	v_lshl_add_u64 v[104:105], v[56:57], 0, v[106:107]
	global_store_short v[104:105], v225, off
	v_mul_f32_e32 v108, v91, v250
	v_fmac_f32_e32 v108, 0x38800000, v84
	v_mul_f32_e32 v108, v98, v108
	v_lshlrev_b32_e32 v109, 16, v245
	v_mul_f32_e32 v108, v108, v109
	v_cvt_pk_bf16_f32 v224, v108, v108
	v_mul_f32_e32 v108, v91, v251
	v_fmac_f32_e32 v108, 0x38800000, v85
	v_mul_f32_e32 v108, v108, v100
	v_lshlrev_b32_e32 v109, 16, v247
	v_mul_f32_e32 v108, v108, v109
	v_cvt_pk_bf16_f32 v225, v108, v108
	v_add_u32_e32 v106, 0x400, v4
	v_lshl_add_u64 v[104:105], v[54:55], 0, v[106:107]
	global_store_short v[104:105], v224, off
	v_lshl_add_u64 v[104:105], v[56:57], 0, v[106:107]
	global_store_short v[104:105], v225, off
	global_load_ushort v240, v1, s[96:97] offset:3072
	global_load_ushort v242, v1, s[74:75] offset:3072
	global_load_ushort v244, v1, s[72:73] offset:3072
	global_load_ushort v246, v1, s[12:13] offset:3072
	global_load_ushort v241, v4, s[96:97] offset:3072
	global_load_ushort v243, v4, s[74:75] offset:3072
	global_load_ushort v245, v4, s[72:73] offset:3072
	global_load_ushort v247, v4, s[12:13] offset:3072
	v_add_u32_e32 v6, 0x7000, v5
	global_load_dwordx2 v[248:249], v6, s[80:81] sc1
	global_load_dwordx2 v[250:251], v6, s[50:51] sc1
	ds_read_b64 v[58:59], v7 offset:448
	ds_read_b64 v[60:61], v8 offset:28672
	ds_read_b64 v[62:63], v8 offset:61440
	ds_read_b64 v[64:65], v9 offset:28672
	ds_read_b64 v[66:67], v9 offset:61440
	s_waitcnt lgkmcnt(5)
	v_pk_mul_f32 v[222:223], v[12:13], v[10:11] op_sel:[1,1] op_sel_hi:[1,0]
	v_pk_fma_f32 v[22:23], v[12:13], v[10:11], v[222:223] op_sel:[0,0,0] op_sel_hi:[0,1,1] neg_lo:[0,0,1]
	v_pk_mul_f32 v[222:223], v[22:23], v[22:23] op_sel:[1,1] op_sel_hi:[1,0]
	v_pk_fma_f32 v[24:25], v[22:23], v[22:23], v[222:223] op_sel:[0,0,0] op_sel_hi:[0,1,1] neg_lo:[0,0,1]
	v_pk_mul_f32 v[222:223], v[24:25], v[22:23] op_sel:[1,1] op_sel_hi:[1,0]
	v_pk_fma_f32 v[26:27], v[24:25], v[22:23], v[222:223] op_sel:[0,0,0] op_sel_hi:[0,1,1] neg_lo:[0,0,1]
	v_pk_mul_f32 v[222:223], v[16:17], v[22:23] op_sel:[1,1] op_sel_hi:[0,1]
	v_pk_fma_f32 v[28:29], v[16:17], v[22:23], v[222:223] op_sel:[0,0,0] op_sel_hi:[1,0,1] neg_hi:[0,0,1]
	v_pk_mul_f32 v[222:223], v[18:19], v[24:25] op_sel:[1,1] op_sel_hi:[0,1]
	v_pk_fma_f32 v[30:31], v[18:19], v[24:25], v[222:223] op_sel:[0,0,0] op_sel_hi:[1,0,1] neg_hi:[0,0,1]
	v_pk_mul_f32 v[222:223], v[20:21], v[26:27] op_sel:[1,1] op_sel_hi:[0,1]
	v_pk_fma_f32 v[68:69], v[20:21], v[26:27], v[222:223] op_sel:[0,0,0] op_sel_hi:[1,0,1] neg_hi:[0,0,1]
	v_pk_add_f32 v[70:71], v[14:15], v[30:31]
	v_pk_add_f32 v[72:73], v[14:15], v[30:31] neg_lo:[0,1] neg_hi:[0,1]
	v_pk_add_f32 v[74:75], v[28:29], v[68:69]
	v_pk_add_f32 v[80:81], v[28:29], v[68:69] neg_lo:[0,1] neg_hi:[0,1]
	v_pk_add_f32 v[82:83], v[70:71], v[74:75]
	v_pk_add_f32 v[84:85], v[72:73], v[80:81] op_sel:[0,1] op_sel_hi:[1,0] neg_lo:[0,1]
	s_waitcnt vmcnt(14)
; __device__ __forceinline__ float bf2f(u16 h){ return __uint_as_float(((unsigned)h)<<16); }
; __device__ __forceinline__ float hconv3(const u16* __restrict__ row, int t, float w0, float w1, float w2, float bias){
;   float m = bf2f(row[t]);
;   int mi=__float_as_int(m);
;   float l=__int_as_float(__builtin_amdgcn_update_dpp(0, mi, 0x138, 0xf, 0xf, false));
;   float r=__int_as_float(__builtin_amdgcn_update_dpp(0, mi, 0x130, 0xf, 0xf, false));
;   return w0*l+w1*m+w2*r+bias;
; __device__ __forceinline__ void phase_hyena(KP kp_, int hf){ asm volatile("" : "+s"(kp_)); const Params p=load_params(kp_);
;     ...
;           _Pragma("unroll 4") for (int i=0;i<8;++i){ int tb=tq+512*i; float2 xr[2]; inv12_half(Z,twA,twB,tb,xr[0],xr[1]);
;             _Pragma("unroll") for (int hh=0;hh<2;++hh){ int t=tb+hh*4096;
;               float x0=hconv3(r2,t,wb0,wb1,wb2,bb_), x1=hconv3(r2+8192,t,wb0,wb1,wb2,bb_);
;               float2 y=xr[hh]; y.x*=(1.f/16384.f); y.y*=(1.f/16384.f); float2 z1=Zs[t];
;               float o0=x0*(y.x+z1.x*bias1)*bf2f(rz[t]); float o1=x1*(y.y+z1.y*bias1)*bf2f(rz[8192+t]);
;               ybT[(size_t)c*16384+t]=f2bf(o0); ybT[(size_t)c*16384+8192+t]=f2bf(o1); } }
	v_lshlrev_b32_e32 v224, 16, v228
	v_mul_f32_e32 v227, v88, v224
	s_nop 0
	v_fmac_f32_dpp v227, v224, v87 wave_shr:1 row_mask:0xf bank_mask:0xf
	v_fmac_f32_dpp v227, v224, v89 wave_shl:1 row_mask:0xf bank_mask:0xf
	v_add_f32_e32 v94, v90, v227
	v_lshlrev_b32_e32 v224, 16, v230
	v_mul_f32_e32 v227, v88, v224
	s_nop 0
	v_fmac_f32_dpp v227, v224, v87 wave_shr:1 row_mask:0xf bank_mask:0xf
	v_fmac_f32_dpp v227, v224, v89 wave_shl:1 row_mask:0xf bank_mask:0xf
	v_add_f32_e32 v97, v90, v227
	v_lshlrev_b32_e32 v224, 16, v229
	v_mul_f32_e32 v227, v88, v224
	s_nop 0
	v_fmac_f32_dpp v227, v224, v87 wave_shr:1 row_mask:0xf bank_mask:0xf
	v_fmac_f32_dpp v227, v224, v89 wave_shl:1 row_mask:0xf bank_mask:0xf
	v_add_f32_e32 v98, v90, v227
	v_lshlrev_b32_e32 v224, 16, v231
	v_mul_f32_e32 v227, v88, v224
	s_nop 0
	v_fmac_f32_dpp v227, v224, v87 wave_shr:1 row_mask:0xf bank_mask:0xf
	v_fmac_f32_dpp v227, v224, v89 wave_shl:1 row_mask:0xf bank_mask:0xf
	v_add_f32_e32 v100, v90, v227
	v_mul_f32_e32 v108, v91, v236
	v_fmac_f32_e32 v108, 0x38800000, v82
	v_mul_f32_e32 v108, v94, v108
	v_lshlrev_b32_e32 v109, 16, v232
	v_mul_f32_e32 v108, v108, v109
	v_cvt_pk_bf16_f32 v224, v108, v108
	v_mul_f32_e32 v108, v91, v237
	v_fmac_f32_e32 v108, 0x38800000, v83
	v_mul_f32_e32 v108, v108, v97
	v_lshlrev_b32_e32 v109, 16, v234
	v_mul_f32_e32 v108, v108, v109
	v_cvt_pk_bf16_f32 v225, v108, v108
	v_add_u32_e32 v106, 0x800, v1
	v_lshl_add_u64 v[104:105], v[54:55], 0, v[106:107]
	global_store_short v[104:105], v224, off
	v_lshl_add_u64 v[104:105], v[56:57], 0, v[106:107]
	global_store_short v[104:105], v225, off
	v_mul_f32_e32 v108, v91, v238
	v_fmac_f32_e32 v108, 0x38800000, v84
	v_mul_f32_e32 v108, v98, v108
	v_lshlrev_b32_e32 v109, 16, v233
	v_mul_f32_e32 v108, v108, v109
	v_cvt_pk_bf16_f32 v224, v108, v108
	v_mul_f32_e32 v108, v91, v239
	v_fmac_f32_e32 v108, 0x38800000, v85
	v_mul_f32_e32 v108, v108, v100
	v_lshlrev_b32_e32 v109, 16, v235
	v_mul_f32_e32 v108, v108, v109
	v_cvt_pk_bf16_f32 v225, v108, v108
	v_add_u32_e32 v106, 0x800, v4
	v_lshl_add_u64 v[104:105], v[54:55], 0, v[106:107]
	global_store_short v[104:105], v224, off
	v_lshl_add_u64 v[104:105], v[56:57], 0, v[106:107]
	global_store_short v[104:105], v225, off
	s_waitcnt lgkmcnt(0)
	v_pk_mul_f32 v[222:223], v[58:59], v[10:11] op_sel:[1,1] op_sel_hi:[1,0]
	v_pk_fma_f32 v[22:23], v[58:59], v[10:11], v[222:223] op_sel:[0,0,0] op_sel_hi:[0,1,1] neg_lo:[0,0,1]
	v_pk_mul_f32 v[222:223], v[22:23], v[22:23] op_sel:[1,1] op_sel_hi:[1,0]
	v_pk_fma_f32 v[24:25], v[22:23], v[22:23], v[222:223] op_sel:[0,0,0] op_sel_hi:[0,1,1] neg_lo:[0,0,1]
	v_pk_mul_f32 v[222:223], v[24:25], v[22:23] op_sel:[1,1] op_sel_hi:[1,0]
	v_pk_fma_f32 v[26:27], v[24:25], v[22:23], v[222:223] op_sel:[0,0,0] op_sel_hi:[0,1,1] neg_lo:[0,0,1]
	v_pk_mul_f32 v[222:223], v[62:63], v[22:23] op_sel:[1,1] op_sel_hi:[0,1]
	v_pk_fma_f32 v[28:29], v[62:63], v[22:23], v[222:223] op_sel:[0,0,0] op_sel_hi:[1,0,1] neg_hi:[0,0,1]
	v_pk_mul_f32 v[222:223], v[64:65], v[24:25] op_sel:[1,1] op_sel_hi:[0,1]
	v_pk_fma_f32 v[30:31], v[64:65], v[24:25], v[222:223] op_sel:[0,0,0] op_sel_hi:[1,0,1] neg_hi:[0,0,1]
	v_pk_mul_f32 v[222:223], v[66:67], v[26:27] op_sel:[1,1] op_sel_hi:[0,1]
	v_pk_fma_f32 v[68:69], v[66:67], v[26:27], v[222:223] op_sel:[0,0,0] op_sel_hi:[1,0,1] neg_hi:[0,0,1]
	v_pk_add_f32 v[70:71], v[60:61], v[30:31]
	v_pk_add_f32 v[72:73], v[60:61], v[30:31] neg_lo:[0,1] neg_hi:[0,1]
	v_pk_add_f32 v[74:75], v[28:29], v[68:69]
	v_pk_add_f32 v[80:81], v[28:29], v[68:69] neg_lo:[0,1] neg_hi:[0,1]
	v_pk_add_f32 v[82:83], v[70:71], v[74:75]
	v_pk_add_f32 v[84:85], v[72:73], v[80:81] op_sel:[0,1] op_sel_hi:[1,0] neg_lo:[0,1]
	s_waitcnt vmcnt(4)
	v_lshlrev_b32_e32 v224, 16, v240
	v_mul_f32_e32 v227, v88, v224
	s_nop 0
	v_fmac_f32_dpp v227, v224, v87 wave_shr:1 row_mask:0xf bank_mask:0xf
	v_fmac_f32_dpp v227, v224, v89 wave_shl:1 row_mask:0xf bank_mask:0xf
	v_add_f32_e32 v94, v90, v227
	v_lshlrev_b32_e32 v224, 16, v242
	v_mul_f32_e32 v227, v88, v224
	s_nop 0
	v_fmac_f32_dpp v227, v224, v87 wave_shr:1 row_mask:0xf bank_mask:0xf
	v_fmac_f32_dpp v227, v224, v89 wave_shl:1 row_mask:0xf bank_mask:0xf
	v_add_f32_e32 v97, v90, v227
	v_lshlrev_b32_e32 v224, 16, v241
	v_mul_f32_e32 v227, v88, v224
	s_nop 0
	v_fmac_f32_dpp v227, v224, v87 wave_shr:1 row_mask:0xf bank_mask:0xf
	v_fmac_f32_dpp v227, v224, v89 wave_shl:1 row_mask:0xf bank_mask:0xf
	v_add_f32_e32 v98, v90, v227
	v_lshlrev_b32_e32 v224, 16, v243
	v_mul_f32_e32 v227, v88, v224
	s_nop 0
	v_fmac_f32_dpp v227, v224, v87 wave_shr:1 row_mask:0xf bank_mask:0xf
	v_fmac_f32_dpp v227, v224, v89 wave_shl:1 row_mask:0xf bank_mask:0xf
	v_add_f32_e32 v100, v90, v227
	v_mul_f32_e32 v108, v91, v248
	v_fmac_f32_e32 v108, 0x38800000, v82
	v_mul_f32_e32 v108, v94, v108
	v_lshlrev_b32_e32 v109, 16, v244
	v_mul_f32_e32 v108, v108, v109
	v_cvt_pk_bf16_f32 v224, v108, v108
	v_mul_f32_e32 v108, v91, v249
	v_fmac_f32_e32 v108, 0x38800000, v83
	v_mul_f32_e32 v108, v108, v97
	v_lshlrev_b32_e32 v109, 16, v246
	v_mul_f32_e32 v108, v108, v109
	v_cvt_pk_bf16_f32 v225, v108, v108
	v_add_u32_e32 v106, 0xc00, v1
	v_lshl_add_u64 v[104:105], v[54:55], 0, v[106:107]
	global_store_short v[104:105], v224, off
	v_lshl_add_u64 v[104:105], v[56:57], 0, v[106:107]
	global_store_short v[104:105], v225, off
	v_mul_f32_e32 v108, v91, v250
	v_fmac_f32_e32 v108, 0x38800000, v84
	v_mul_f32_e32 v108, v98, v108
	v_lshlrev_b32_e32 v109, 16, v245
	v_mul_f32_e32 v108, v108, v109
	v_cvt_pk_bf16_f32 v224, v108, v108
	v_mul_f32_e32 v108, v91, v251
	v_fmac_f32_e32 v108, 0x38800000, v85
	v_mul_f32_e32 v108, v108, v100
	v_lshlrev_b32_e32 v109, 16, v247
	v_mul_f32_e32 v108, v108, v109
	v_cvt_pk_bf16_f32 v225, v108, v108
	v_add_u32_e32 v106, 0xc00, v4
	v_lshl_add_u64 v[104:105], v[54:55], 0, v[106:107]
	global_store_short v[104:105], v224, off
	v_lshl_add_u64 v[104:105], v[56:57], 0, v[106:107]
	global_store_short v[104:105], v225, off
	s_mov_b32 s50, 0x2000
	s_mov_b32 s51, 0
	s_mov_b64 s[12:13], 0
